# PH0 adaLN GEMV slice: 32-64 weight loads in flight per wave instead of 4, packed FMAs
# baseline (speedup 1.0000x reference)
.LBB0_29:
	s_mov_b64 s[8:9], 0x6000
	v_mad_i64_i32 v[2:3], s[6:7], v34, s42, v[18:19]
	v_lshlrev_b32_e32 v4, 2, v34
	global_load_dword v134, v[2:3], off
	v_lshl_add_u64 v[2:3], v[2:3], 0, s[8:9]
	global_load_dword v135, v[2:3], off
	v_lshl_add_u64 v[2:3], v[2:3], 0, s[8:9]
	global_load_dword v136, v[2:3], off
	v_lshl_add_u64 v[2:3], v[2:3], 0, s[8:9]
	global_load_dword v137, v[2:3], off
	v_lshl_add_u64 v[2:3], v[2:3], 0, s[8:9]
	global_load_dword v138, v[2:3], off
	v_lshl_add_u64 v[2:3], v[2:3], 0, s[8:9]
	global_load_dword v139, v[2:3], off
	v_lshl_add_u64 v[2:3], v[2:3], 0, s[8:9]
	global_load_dword v140, v[2:3], off
	v_lshl_add_u64 v[2:3], v[2:3], 0, s[8:9]
	global_load_dword v141, v[2:3], off
	v_lshl_add_u64 v[2:3], v[2:3], 0, s[8:9]
	global_load_dword v142, v[2:3], off
	v_lshl_add_u64 v[2:3], v[2:3], 0, s[8:9]
	global_load_dword v143, v[2:3], off
	v_lshl_add_u64 v[2:3], v[2:3], 0, s[8:9]
	global_load_dword v144, v[2:3], off
	v_lshl_add_u64 v[2:3], v[2:3], 0, s[8:9]
	global_load_dword v145, v[2:3], off
	v_lshl_add_u64 v[2:3], v[2:3], 0, s[8:9]
	global_load_dword v146, v[2:3], off
	v_lshl_add_u64 v[2:3], v[2:3], 0, s[8:9]
	global_load_dword v147, v[2:3], off
	v_lshl_add_u64 v[2:3], v[2:3], 0, s[8:9]
	global_load_dword v148, v[2:3], off
	v_lshl_add_u64 v[2:3], v[2:3], 0, s[8:9]
	global_load_dword v149, v[2:3], off
	v_lshl_add_u64 v[2:3], v[2:3], 0, s[8:9]
	global_load_dword v150, v[2:3], off
	v_lshl_add_u64 v[2:3], v[2:3], 0, s[8:9]
	global_load_dword v151, v[2:3], off
	v_lshl_add_u64 v[2:3], v[2:3], 0, s[8:9]
	global_load_dword v152, v[2:3], off
	v_lshl_add_u64 v[2:3], v[2:3], 0, s[8:9]
	global_load_dword v153, v[2:3], off
	v_lshl_add_u64 v[2:3], v[2:3], 0, s[8:9]
	global_load_dword v154, v[2:3], off
	v_lshl_add_u64 v[2:3], v[2:3], 0, s[8:9]
	global_load_dword v155, v[2:3], off
	v_lshl_add_u64 v[2:3], v[2:3], 0, s[8:9]
	global_load_dword v156, v[2:3], off
	v_lshl_add_u64 v[2:3], v[2:3], 0, s[8:9]
	global_load_dword v157, v[2:3], off
	v_lshl_add_u64 v[2:3], v[2:3], 0, s[8:9]
	global_load_dword v158, v[2:3], off
	v_lshl_add_u64 v[2:3], v[2:3], 0, s[8:9]
	global_load_dword v159, v[2:3], off
	v_lshl_add_u64 v[2:3], v[2:3], 0, s[8:9]
	global_load_dword v160, v[2:3], off
	v_lshl_add_u64 v[2:3], v[2:3], 0, s[8:9]
	global_load_dword v161, v[2:3], off
	v_lshl_add_u64 v[2:3], v[2:3], 0, s[8:9]
	global_load_dword v162, v[2:3], off
	v_lshl_add_u64 v[2:3], v[2:3], 0, s[8:9]
	global_load_dword v163, v[2:3], off
	v_lshl_add_u64 v[2:3], v[2:3], 0, s[8:9]
	global_load_dword v164, v[2:3], off
	v_lshl_add_u64 v[2:3], v[2:3], 0, s[8:9]
	global_load_dword v165, v[2:3], off
	v_lshl_add_u64 v[2:3], v[2:3], 0, s[8:9]
	ds_read_b128 v[54:57], v4 offset:0
	ds_read_b128 v[58:61], v4 offset:4096
	ds_read_b128 v[62:65], v4 offset:8192
	ds_read_b128 v[66:69], v4 offset:12288
	ds_read_b128 v[70:73], v4 offset:16384
	global_load_dword v172, v[2:3], off
	v_lshl_add_u64 v[2:3], v[2:3], 0, s[8:9]
	global_load_dword v173, v[2:3], off
	v_lshl_add_u64 v[2:3], v[2:3], 0, s[8:9]
	global_load_dword v174, v[2:3], off
	v_lshl_add_u64 v[2:3], v[2:3], 0, s[8:9]
	global_load_dword v175, v[2:3], off
	v_lshl_add_u64 v[2:3], v[2:3], 0, s[8:9]
	global_load_dword v176, v[2:3], off
	v_lshl_add_u64 v[2:3], v[2:3], 0, s[8:9]
	global_load_dword v177, v[2:3], off
	v_lshl_add_u64 v[2:3], v[2:3], 0, s[8:9]
	global_load_dword v178, v[2:3], off
	v_lshl_add_u64 v[2:3], v[2:3], 0, s[8:9]
	global_load_dword v179, v[2:3], off
	v_lshl_add_u64 v[2:3], v[2:3], 0, s[8:9]
	global_load_dword v180, v[2:3], off
	v_lshl_add_u64 v[2:3], v[2:3], 0, s[8:9]
	global_load_dword v181, v[2:3], off
	v_lshl_add_u64 v[2:3], v[2:3], 0, s[8:9]
	global_load_dword v182, v[2:3], off
	v_lshl_add_u64 v[2:3], v[2:3], 0, s[8:9]
	global_load_dword v183, v[2:3], off
	v_lshl_add_u64 v[2:3], v[2:3], 0, s[8:9]
	global_load_dword v184, v[2:3], off
	v_lshl_add_u64 v[2:3], v[2:3], 0, s[8:9]
	global_load_dword v185, v[2:3], off
	v_lshl_add_u64 v[2:3], v[2:3], 0, s[8:9]
	global_load_dword v186, v[2:3], off
	v_lshl_add_u64 v[2:3], v[2:3], 0, s[8:9]
	global_load_dword v187, v[2:3], off
	v_lshl_add_u64 v[2:3], v[2:3], 0, s[8:9]
	global_load_dword v188, v[2:3], off
	v_lshl_add_u64 v[2:3], v[2:3], 0, s[8:9]
	global_load_dword v189, v[2:3], off
	v_lshl_add_u64 v[2:3], v[2:3], 0, s[8:9]
	global_load_dword v190, v[2:3], off
	v_lshl_add_u64 v[2:3], v[2:3], 0, s[8:9]
	global_load_dword v191, v[2:3], off
	v_lshl_add_u64 v[2:3], v[2:3], 0, s[8:9]
	global_load_dword v192, v[2:3], off
	v_lshl_add_u64 v[2:3], v[2:3], 0, s[8:9]
	global_load_dword v193, v[2:3], off
	v_lshl_add_u64 v[2:3], v[2:3], 0, s[8:9]
	global_load_dword v194, v[2:3], off
	v_lshl_add_u64 v[2:3], v[2:3], 0, s[8:9]
	global_load_dword v195, v[2:3], off
	v_lshl_add_u64 v[2:3], v[2:3], 0, s[8:9]
	global_load_dword v196, v[2:3], off
	v_lshl_add_u64 v[2:3], v[2:3], 0, s[8:9]
	global_load_dword v197, v[2:3], off
	v_lshl_add_u64 v[2:3], v[2:3], 0, s[8:9]
	global_load_dword v198, v[2:3], off
	v_lshl_add_u64 v[2:3], v[2:3], 0, s[8:9]
	global_load_dword v199, v[2:3], off
	v_lshl_add_u64 v[2:3], v[2:3], 0, s[8:9]
	global_load_dword v200, v[2:3], off
	v_lshl_add_u64 v[2:3], v[2:3], 0, s[8:9]
	global_load_dword v201, v[2:3], off
	v_lshl_add_u64 v[2:3], v[2:3], 0, s[8:9]
	global_load_dword v202, v[2:3], off
	v_lshl_add_u64 v[2:3], v[2:3], 0, s[8:9]
	global_load_dword v203, v[2:3], off
	v_lshl_add_u64 v[2:3], v[2:3], 0, s[8:9]
	s_waitcnt vmcnt(32)
	ds_read_b128 v[74:77], v4 offset:16
	ds_read_b128 v[78:81], v4 offset:4112
	ds_read_b128 v[82:85], v4 offset:8208
	ds_read_b128 v[86:89], v4 offset:12304
	ds_read_b128 v[90:93], v4 offset:16400
	s_waitcnt lgkmcnt(5)
	v_pk_mul_f32 v[94:95], v[54:55], v[134:135]
	v_pk_fma_f32 v[94:95], v[56:57], v[136:137], v[94:95]
	v_pk_mul_f32 v[96:97], v[58:59], v[134:135]
	v_pk_fma_f32 v[96:97], v[60:61], v[136:137], v[96:97]
	v_pk_mul_f32 v[98:99], v[62:63], v[134:135]
	v_pk_fma_f32 v[98:99], v[64:65], v[136:137], v[98:99]
	v_pk_mul_f32 v[100:101], v[66:67], v[134:135]
	v_pk_fma_f32 v[100:101], v[68:69], v[136:137], v[100:101]
	v_pk_mul_f32 v[102:103], v[70:71], v[134:135]
	v_pk_fma_f32 v[102:103], v[72:73], v[136:137], v[102:103]
	ds_read_b128 v[54:57], v4 offset:32
	ds_read_b128 v[58:61], v4 offset:4128
	ds_read_b128 v[62:65], v4 offset:8224
	ds_read_b128 v[66:69], v4 offset:12320
	ds_read_b128 v[70:73], v4 offset:16416
	s_waitcnt lgkmcnt(5)
	v_pk_fma_f32 v[94:95], v[74:75], v[138:139], v[94:95]
	v_pk_fma_f32 v[94:95], v[76:77], v[140:141], v[94:95]
	v_pk_fma_f32 v[96:97], v[78:79], v[138:139], v[96:97]
	v_pk_fma_f32 v[96:97], v[80:81], v[140:141], v[96:97]
	v_pk_fma_f32 v[98:99], v[82:83], v[138:139], v[98:99]
	v_pk_fma_f32 v[98:99], v[84:85], v[140:141], v[98:99]
	v_pk_fma_f32 v[100:101], v[86:87], v[138:139], v[100:101]
	v_pk_fma_f32 v[100:101], v[88:89], v[140:141], v[100:101]
	v_pk_fma_f32 v[102:103], v[90:91], v[138:139], v[102:103]
	v_pk_fma_f32 v[102:103], v[92:93], v[140:141], v[102:103]
	ds_read_b128 v[74:77], v4 offset:48
	ds_read_b128 v[78:81], v4 offset:4144
	ds_read_b128 v[82:85], v4 offset:8240
	ds_read_b128 v[86:89], v4 offset:12336
	ds_read_b128 v[90:93], v4 offset:16432
	s_waitcnt lgkmcnt(5)
	v_pk_fma_f32 v[94:95], v[54:55], v[142:143], v[94:95]
	v_pk_fma_f32 v[94:95], v[56:57], v[144:145], v[94:95]
	v_pk_fma_f32 v[96:97], v[58:59], v[142:143], v[96:97]
	v_pk_fma_f32 v[96:97], v[60:61], v[144:145], v[96:97]
	v_pk_fma_f32 v[98:99], v[62:63], v[142:143], v[98:99]
	v_pk_fma_f32 v[98:99], v[64:65], v[144:145], v[98:99]
	v_pk_fma_f32 v[100:101], v[66:67], v[142:143], v[100:101]
	v_pk_fma_f32 v[100:101], v[68:69], v[144:145], v[100:101]
	v_pk_fma_f32 v[102:103], v[70:71], v[142:143], v[102:103]
	v_pk_fma_f32 v[102:103], v[72:73], v[144:145], v[102:103]
	ds_read_b128 v[54:57], v4 offset:64
	ds_read_b128 v[58:61], v4 offset:4160
	ds_read_b128 v[62:65], v4 offset:8256
	ds_read_b128 v[66:69], v4 offset:12352
	ds_read_b128 v[70:73], v4 offset:16448
	s_waitcnt lgkmcnt(5)
	v_pk_fma_f32 v[94:95], v[74:75], v[146:147], v[94:95]
	v_pk_fma_f32 v[94:95], v[76:77], v[148:149], v[94:95]
	v_pk_fma_f32 v[96:97], v[78:79], v[146:147], v[96:97]
	v_pk_fma_f32 v[96:97], v[80:81], v[148:149], v[96:97]
	v_pk_fma_f32 v[98:99], v[82:83], v[146:147], v[98:99]
	v_pk_fma_f32 v[98:99], v[84:85], v[148:149], v[98:99]
	v_pk_fma_f32 v[100:101], v[86:87], v[146:147], v[100:101]
	v_pk_fma_f32 v[100:101], v[88:89], v[148:149], v[100:101]
	v_pk_fma_f32 v[102:103], v[90:91], v[146:147], v[102:103]
	v_pk_fma_f32 v[102:103], v[92:93], v[148:149], v[102:103]
	ds_read_b128 v[74:77], v4 offset:80
	ds_read_b128 v[78:81], v4 offset:4176
	ds_read_b128 v[82:85], v4 offset:8272
	ds_read_b128 v[86:89], v4 offset:12368
	ds_read_b128 v[90:93], v4 offset:16464
	s_waitcnt lgkmcnt(5)
	v_pk_fma_f32 v[94:95], v[54:55], v[150:151], v[94:95]
	v_pk_fma_f32 v[94:95], v[56:57], v[152:153], v[94:95]
	v_pk_fma_f32 v[96:97], v[58:59], v[150:151], v[96:97]
	v_pk_fma_f32 v[96:97], v[60:61], v[152:153], v[96:97]
	v_pk_fma_f32 v[98:99], v[62:63], v[150:151], v[98:99]
	v_pk_fma_f32 v[98:99], v[64:65], v[152:153], v[98:99]
	v_pk_fma_f32 v[100:101], v[66:67], v[150:151], v[100:101]
	v_pk_fma_f32 v[100:101], v[68:69], v[152:153], v[100:101]
	v_pk_fma_f32 v[102:103], v[70:71], v[150:151], v[102:103]
	v_pk_fma_f32 v[102:103], v[72:73], v[152:153], v[102:103]
	ds_read_b128 v[54:57], v4 offset:96
	ds_read_b128 v[58:61], v4 offset:4192
	ds_read_b128 v[62:65], v4 offset:8288
	ds_read_b128 v[66:69], v4 offset:12384
	ds_read_b128 v[70:73], v4 offset:16480
	s_waitcnt lgkmcnt(5)
	v_pk_fma_f32 v[94:95], v[74:75], v[154:155], v[94:95]
	v_pk_fma_f32 v[94:95], v[76:77], v[156:157], v[94:95]
	v_pk_fma_f32 v[96:97], v[78:79], v[154:155], v[96:97]
	v_pk_fma_f32 v[96:97], v[80:81], v[156:157], v[96:97]
	v_pk_fma_f32 v[98:99], v[82:83], v[154:155], v[98:99]
	v_pk_fma_f32 v[98:99], v[84:85], v[156:157], v[98:99]
	v_pk_fma_f32 v[100:101], v[86:87], v[154:155], v[100:101]
	v_pk_fma_f32 v[100:101], v[88:89], v[156:157], v[100:101]
	v_pk_fma_f32 v[102:103], v[90:91], v[154:155], v[102:103]
	v_pk_fma_f32 v[102:103], v[92:93], v[156:157], v[102:103]
	ds_read_b128 v[74:77], v4 offset:112
	ds_read_b128 v[78:81], v4 offset:4208
	ds_read_b128 v[82:85], v4 offset:8304
	ds_read_b128 v[86:89], v4 offset:12400
	ds_read_b128 v[90:93], v4 offset:16496
	s_waitcnt lgkmcnt(5)
	v_pk_fma_f32 v[94:95], v[54:55], v[158:159], v[94:95]
	v_pk_fma_f32 v[94:95], v[56:57], v[160:161], v[94:95]
	v_pk_fma_f32 v[96:97], v[58:59], v[158:159], v[96:97]
	v_pk_fma_f32 v[96:97], v[60:61], v[160:161], v[96:97]
	v_pk_fma_f32 v[98:99], v[62:63], v[158:159], v[98:99]
	v_pk_fma_f32 v[98:99], v[64:65], v[160:161], v[98:99]
	v_pk_fma_f32 v[100:101], v[66:67], v[158:159], v[100:101]
	v_pk_fma_f32 v[100:101], v[68:69], v[160:161], v[100:101]
	v_pk_fma_f32 v[102:103], v[70:71], v[158:159], v[102:103]
	v_pk_fma_f32 v[102:103], v[72:73], v[160:161], v[102:103]
	ds_read_b128 v[54:57], v4 offset:128
	ds_read_b128 v[58:61], v4 offset:4224
	ds_read_b128 v[62:65], v4 offset:8320
	ds_read_b128 v[66:69], v4 offset:12416
	ds_read_b128 v[70:73], v4 offset:16512
	s_waitcnt lgkmcnt(5)
	v_pk_fma_f32 v[94:95], v[74:75], v[162:163], v[94:95]
	v_pk_fma_f32 v[94:95], v[76:77], v[164:165], v[94:95]
	v_pk_fma_f32 v[96:97], v[78:79], v[162:163], v[96:97]
	v_pk_fma_f32 v[96:97], v[80:81], v[164:165], v[96:97]
	v_pk_fma_f32 v[98:99], v[82:83], v[162:163], v[98:99]
	v_pk_fma_f32 v[98:99], v[84:85], v[164:165], v[98:99]
	v_pk_fma_f32 v[100:101], v[86:87], v[162:163], v[100:101]
	v_pk_fma_f32 v[100:101], v[88:89], v[164:165], v[100:101]
	v_pk_fma_f32 v[102:103], v[90:91], v[162:163], v[102:103]
	v_pk_fma_f32 v[102:103], v[92:93], v[164:165], v[102:103]
	global_load_dword v134, v[2:3], off
	v_lshl_add_u64 v[2:3], v[2:3], 0, s[8:9]
	global_load_dword v135, v[2:3], off
	v_lshl_add_u64 v[2:3], v[2:3], 0, s[8:9]
	global_load_dword v136, v[2:3], off
	v_lshl_add_u64 v[2:3], v[2:3], 0, s[8:9]
	global_load_dword v137, v[2:3], off
	v_lshl_add_u64 v[2:3], v[2:3], 0, s[8:9]
	global_load_dword v138, v[2:3], off
	v_lshl_add_u64 v[2:3], v[2:3], 0, s[8:9]
	global_load_dword v139, v[2:3], off
	v_lshl_add_u64 v[2:3], v[2:3], 0, s[8:9]
	global_load_dword v140, v[2:3], off
	v_lshl_add_u64 v[2:3], v[2:3], 0, s[8:9]
	global_load_dword v141, v[2:3], off
	v_lshl_add_u64 v[2:3], v[2:3], 0, s[8:9]
	global_load_dword v142, v[2:3], off
	v_lshl_add_u64 v[2:3], v[2:3], 0, s[8:9]
	global_load_dword v143, v[2:3], off
	v_lshl_add_u64 v[2:3], v[2:3], 0, s[8:9]
	global_load_dword v144, v[2:3], off
	v_lshl_add_u64 v[2:3], v[2:3], 0, s[8:9]
	global_load_dword v145, v[2:3], off
	v_lshl_add_u64 v[2:3], v[2:3], 0, s[8:9]
	global_load_dword v146, v[2:3], off
	v_lshl_add_u64 v[2:3], v[2:3], 0, s[8:9]
	global_load_dword v147, v[2:3], off
	v_lshl_add_u64 v[2:3], v[2:3], 0, s[8:9]
	global_load_dword v148, v[2:3], off
	v_lshl_add_u64 v[2:3], v[2:3], 0, s[8:9]
	global_load_dword v149, v[2:3], off
	v_lshl_add_u64 v[2:3], v[2:3], 0, s[8:9]
	global_load_dword v150, v[2:3], off
	v_lshl_add_u64 v[2:3], v[2:3], 0, s[8:9]
	global_load_dword v151, v[2:3], off
	v_lshl_add_u64 v[2:3], v[2:3], 0, s[8:9]
	global_load_dword v152, v[2:3], off
	v_lshl_add_u64 v[2:3], v[2:3], 0, s[8:9]
	global_load_dword v153, v[2:3], off
	v_lshl_add_u64 v[2:3], v[2:3], 0, s[8:9]
	global_load_dword v154, v[2:3], off
	v_lshl_add_u64 v[2:3], v[2:3], 0, s[8:9]
	global_load_dword v155, v[2:3], off
	v_lshl_add_u64 v[2:3], v[2:3], 0, s[8:9]
	global_load_dword v156, v[2:3], off
	v_lshl_add_u64 v[2:3], v[2:3], 0, s[8:9]
	global_load_dword v157, v[2:3], off
	v_lshl_add_u64 v[2:3], v[2:3], 0, s[8:9]
	global_load_dword v158, v[2:3], off
	v_lshl_add_u64 v[2:3], v[2:3], 0, s[8:9]
	global_load_dword v159, v[2:3], off
	v_lshl_add_u64 v[2:3], v[2:3], 0, s[8:9]
	global_load_dword v160, v[2:3], off
	v_lshl_add_u64 v[2:3], v[2:3], 0, s[8:9]
	global_load_dword v161, v[2:3], off
	v_lshl_add_u64 v[2:3], v[2:3], 0, s[8:9]
	global_load_dword v162, v[2:3], off
	v_lshl_add_u64 v[2:3], v[2:3], 0, s[8:9]
	global_load_dword v163, v[2:3], off
	v_lshl_add_u64 v[2:3], v[2:3], 0, s[8:9]
	global_load_dword v164, v[2:3], off
	v_lshl_add_u64 v[2:3], v[2:3], 0, s[8:9]
	global_load_dword v165, v[2:3], off
	v_lshl_add_u64 v[2:3], v[2:3], 0, s[8:9]
	s_waitcnt vmcnt(32)
	ds_read_b128 v[74:77], v4 offset:144
	ds_read_b128 v[78:81], v4 offset:4240
	ds_read_b128 v[82:85], v4 offset:8336
	ds_read_b128 v[86:89], v4 offset:12432
	ds_read_b128 v[90:93], v4 offset:16528
	s_waitcnt lgkmcnt(5)
	v_pk_fma_f32 v[94:95], v[54:55], v[172:173], v[94:95]
	v_pk_fma_f32 v[94:95], v[56:57], v[174:175], v[94:95]
	v_pk_fma_f32 v[96:97], v[58:59], v[172:173], v[96:97]
	v_pk_fma_f32 v[96:97], v[60:61], v[174:175], v[96:97]
	v_pk_fma_f32 v[98:99], v[62:63], v[172:173], v[98:99]
	v_pk_fma_f32 v[98:99], v[64:65], v[174:175], v[98:99]
	v_pk_fma_f32 v[100:101], v[66:67], v[172:173], v[100:101]
	v_pk_fma_f32 v[100:101], v[68:69], v[174:175], v[100:101]
	v_pk_fma_f32 v[102:103], v[70:71], v[172:173], v[102:103]
	v_pk_fma_f32 v[102:103], v[72:73], v[174:175], v[102:103]
	ds_read_b128 v[54:57], v4 offset:160
	ds_read_b128 v[58:61], v4 offset:4256
	ds_read_b128 v[62:65], v4 offset:8352
	ds_read_b128 v[66:69], v4 offset:12448
	ds_read_b128 v[70:73], v4 offset:16544
	s_waitcnt lgkmcnt(5)
	v_pk_fma_f32 v[94:95], v[74:75], v[176:177], v[94:95]
	v_pk_fma_f32 v[94:95], v[76:77], v[178:179], v[94:95]
	v_pk_fma_f32 v[96:97], v[78:79], v[176:177], v[96:97]
	v_pk_fma_f32 v[96:97], v[80:81], v[178:179], v[96:97]
	v_pk_fma_f32 v[98:99], v[82:83], v[176:177], v[98:99]
	v_pk_fma_f32 v[98:99], v[84:85], v[178:179], v[98:99]
	v_pk_fma_f32 v[100:101], v[86:87], v[176:177], v[100:101]
	v_pk_fma_f32 v[100:101], v[88:89], v[178:179], v[100:101]
	v_pk_fma_f32 v[102:103], v[90:91], v[176:177], v[102:103]
	v_pk_fma_f32 v[102:103], v[92:93], v[178:179], v[102:103]
	ds_read_b128 v[74:77], v4 offset:176
	ds_read_b128 v[78:81], v4 offset:4272
	ds_read_b128 v[82:85], v4 offset:8368
	ds_read_b128 v[86:89], v4 offset:12464
	ds_read_b128 v[90:93], v4 offset:16560
	s_waitcnt lgkmcnt(5)
	v_pk_fma_f32 v[94:95], v[54:55], v[180:181], v[94:95]
	v_pk_fma_f32 v[94:95], v[56:57], v[182:183], v[94:95]
	v_pk_fma_f32 v[96:97], v[58:59], v[180:181], v[96:97]
	v_pk_fma_f32 v[96:97], v[60:61], v[182:183], v[96:97]
	v_pk_fma_f32 v[98:99], v[62:63], v[180:181], v[98:99]
	v_pk_fma_f32 v[98:99], v[64:65], v[182:183], v[98:99]
	v_pk_fma_f32 v[100:101], v[66:67], v[180:181], v[100:101]
	v_pk_fma_f32 v[100:101], v[68:69], v[182:183], v[100:101]
	v_pk_fma_f32 v[102:103], v[70:71], v[180:181], v[102:103]
	v_pk_fma_f32 v[102:103], v[72:73], v[182:183], v[102:103]
	ds_read_b128 v[54:57], v4 offset:192
	ds_read_b128 v[58:61], v4 offset:4288
	ds_read_b128 v[62:65], v4 offset:8384
	ds_read_b128 v[66:69], v4 offset:12480
	ds_read_b128 v[70:73], v4 offset:16576
	s_waitcnt lgkmcnt(5)
	v_pk_fma_f32 v[94:95], v[74:75], v[184:185], v[94:95]
	v_pk_fma_f32 v[94:95], v[76:77], v[186:187], v[94:95]
	v_pk_fma_f32 v[96:97], v[78:79], v[184:185], v[96:97]
	v_pk_fma_f32 v[96:97], v[80:81], v[186:187], v[96:97]
	v_pk_fma_f32 v[98:99], v[82:83], v[184:185], v[98:99]
	v_pk_fma_f32 v[98:99], v[84:85], v[186:187], v[98:99]
	v_pk_fma_f32 v[100:101], v[86:87], v[184:185], v[100:101]
	v_pk_fma_f32 v[100:101], v[88:89], v[186:187], v[100:101]
	v_pk_fma_f32 v[102:103], v[90:91], v[184:185], v[102:103]
	v_pk_fma_f32 v[102:103], v[92:93], v[186:187], v[102:103]
	ds_read_b128 v[74:77], v4 offset:208
	ds_read_b128 v[78:81], v4 offset:4304
	ds_read_b128 v[82:85], v4 offset:8400
	ds_read_b128 v[86:89], v4 offset:12496
	ds_read_b128 v[90:93], v4 offset:16592
	s_waitcnt lgkmcnt(5)
	v_pk_fma_f32 v[94:95], v[54:55], v[188:189], v[94:95]
	v_pk_fma_f32 v[94:95], v[56:57], v[190:191], v[94:95]
	v_pk_fma_f32 v[96:97], v[58:59], v[188:189], v[96:97]
	v_pk_fma_f32 v[96:97], v[60:61], v[190:191], v[96:97]
	v_pk_fma_f32 v[98:99], v[62:63], v[188:189], v[98:99]
	v_pk_fma_f32 v[98:99], v[64:65], v[190:191], v[98:99]
	v_pk_fma_f32 v[100:101], v[66:67], v[188:189], v[100:101]
	v_pk_fma_f32 v[100:101], v[68:69], v[190:191], v[100:101]
	v_pk_fma_f32 v[102:103], v[70:71], v[188:189], v[102:103]
	v_pk_fma_f32 v[102:103], v[72:73], v[190:191], v[102:103]
	ds_read_b128 v[54:57], v4 offset:224
	ds_read_b128 v[58:61], v4 offset:4320
	ds_read_b128 v[62:65], v4 offset:8416
	ds_read_b128 v[66:69], v4 offset:12512
	ds_read_b128 v[70:73], v4 offset:16608
	s_waitcnt lgkmcnt(5)
	v_pk_fma_f32 v[94:95], v[74:75], v[192:193], v[94:95]
	v_pk_fma_f32 v[94:95], v[76:77], v[194:195], v[94:95]
	v_pk_fma_f32 v[96:97], v[78:79], v[192:193], v[96:97]
	v_pk_fma_f32 v[96:97], v[80:81], v[194:195], v[96:97]
	v_pk_fma_f32 v[98:99], v[82:83], v[192:193], v[98:99]
	v_pk_fma_f32 v[98:99], v[84:85], v[194:195], v[98:99]
	v_pk_fma_f32 v[100:101], v[86:87], v[192:193], v[100:101]
	v_pk_fma_f32 v[100:101], v[88:89], v[194:195], v[100:101]
	v_pk_fma_f32 v[102:103], v[90:91], v[192:193], v[102:103]
	v_pk_fma_f32 v[102:103], v[92:93], v[194:195], v[102:103]
	ds_read_b128 v[74:77], v4 offset:240
	ds_read_b128 v[78:81], v4 offset:4336
	ds_read_b128 v[82:85], v4 offset:8432
	ds_read_b128 v[86:89], v4 offset:12528
	ds_read_b128 v[90:93], v4 offset:16624
	s_waitcnt lgkmcnt(5)
	v_pk_fma_f32 v[94:95], v[54:55], v[196:197], v[94:95]
	v_pk_fma_f32 v[94:95], v[56:57], v[198:199], v[94:95]
	v_pk_fma_f32 v[96:97], v[58:59], v[196:197], v[96:97]
	v_pk_fma_f32 v[96:97], v[60:61], v[198:199], v[96:97]
	v_pk_fma_f32 v[98:99], v[62:63], v[196:197], v[98:99]
	v_pk_fma_f32 v[98:99], v[64:65], v[198:199], v[98:99]
	v_pk_fma_f32 v[100:101], v[66:67], v[196:197], v[100:101]
	v_pk_fma_f32 v[100:101], v[68:69], v[198:199], v[100:101]
	v_pk_fma_f32 v[102:103], v[70:71], v[196:197], v[102:103]
	v_pk_fma_f32 v[102:103], v[72:73], v[198:199], v[102:103]
	ds_read_b128 v[54:57], v4 offset:256
	ds_read_b128 v[58:61], v4 offset:4352
	ds_read_b128 v[62:65], v4 offset:8448
	ds_read_b128 v[66:69], v4 offset:12544
	ds_read_b128 v[70:73], v4 offset:16640
	s_waitcnt lgkmcnt(5)
	v_pk_fma_f32 v[94:95], v[74:75], v[200:201], v[94:95]
	v_pk_fma_f32 v[94:95], v[76:77], v[202:203], v[94:95]
	v_pk_fma_f32 v[96:97], v[78:79], v[200:201], v[96:97]
	v_pk_fma_f32 v[96:97], v[80:81], v[202:203], v[96:97]
	v_pk_fma_f32 v[98:99], v[82:83], v[200:201], v[98:99]
	v_pk_fma_f32 v[98:99], v[84:85], v[202:203], v[98:99]
	v_pk_fma_f32 v[100:101], v[86:87], v[200:201], v[100:101]
	v_pk_fma_f32 v[100:101], v[88:89], v[202:203], v[100:101]
	v_pk_fma_f32 v[102:103], v[90:91], v[200:201], v[102:103]
	v_pk_fma_f32 v[102:103], v[92:93], v[202:203], v[102:103]
	global_load_dword v172, v[2:3], off
	v_lshl_add_u64 v[2:3], v[2:3], 0, s[8:9]
	global_load_dword v173, v[2:3], off
	v_lshl_add_u64 v[2:3], v[2:3], 0, s[8:9]
	global_load_dword v174, v[2:3], off
	v_lshl_add_u64 v[2:3], v[2:3], 0, s[8:9]
	global_load_dword v175, v[2:3], off
	v_lshl_add_u64 v[2:3], v[2:3], 0, s[8:9]
	global_load_dword v176, v[2:3], off
	v_lshl_add_u64 v[2:3], v[2:3], 0, s[8:9]
	global_load_dword v177, v[2:3], off
	v_lshl_add_u64 v[2:3], v[2:3], 0, s[8:9]
	global_load_dword v178, v[2:3], off
	v_lshl_add_u64 v[2:3], v[2:3], 0, s[8:9]
	global_load_dword v179, v[2:3], off
	v_lshl_add_u64 v[2:3], v[2:3], 0, s[8:9]
	global_load_dword v180, v[2:3], off
	v_lshl_add_u64 v[2:3], v[2:3], 0, s[8:9]
	global_load_dword v181, v[2:3], off
	v_lshl_add_u64 v[2:3], v[2:3], 0, s[8:9]
	global_load_dword v182, v[2:3], off
	v_lshl_add_u64 v[2:3], v[2:3], 0, s[8:9]
	global_load_dword v183, v[2:3], off
	v_lshl_add_u64 v[2:3], v[2:3], 0, s[8:9]
	global_load_dword v184, v[2:3], off
	v_lshl_add_u64 v[2:3], v[2:3], 0, s[8:9]
	global_load_dword v185, v[2:3], off
	v_lshl_add_u64 v[2:3], v[2:3], 0, s[8:9]
	global_load_dword v186, v[2:3], off
	v_lshl_add_u64 v[2:3], v[2:3], 0, s[8:9]
	global_load_dword v187, v[2:3], off
	v_lshl_add_u64 v[2:3], v[2:3], 0, s[8:9]
	global_load_dword v188, v[2:3], off
	v_lshl_add_u64 v[2:3], v[2:3], 0, s[8:9]
	global_load_dword v189, v[2:3], off
	v_lshl_add_u64 v[2:3], v[2:3], 0, s[8:9]
	global_load_dword v190, v[2:3], off
	v_lshl_add_u64 v[2:3], v[2:3], 0, s[8:9]
	global_load_dword v191, v[2:3], off
	v_lshl_add_u64 v[2:3], v[2:3], 0, s[8:9]
	global_load_dword v192, v[2:3], off
	v_lshl_add_u64 v[2:3], v[2:3], 0, s[8:9]
	global_load_dword v193, v[2:3], off
	v_lshl_add_u64 v[2:3], v[2:3], 0, s[8:9]
	global_load_dword v194, v[2:3], off
	v_lshl_add_u64 v[2:3], v[2:3], 0, s[8:9]
	global_load_dword v195, v[2:3], off
	v_lshl_add_u64 v[2:3], v[2:3], 0, s[8:9]
	global_load_dword v196, v[2:3], off
	v_lshl_add_u64 v[2:3], v[2:3], 0, s[8:9]
	global_load_dword v197, v[2:3], off
	v_lshl_add_u64 v[2:3], v[2:3], 0, s[8:9]
	global_load_dword v198, v[2:3], off
	v_lshl_add_u64 v[2:3], v[2:3], 0, s[8:9]
	global_load_dword v199, v[2:3], off
	v_lshl_add_u64 v[2:3], v[2:3], 0, s[8:9]
	global_load_dword v200, v[2:3], off
	v_lshl_add_u64 v[2:3], v[2:3], 0, s[8:9]
	global_load_dword v201, v[2:3], off
	v_lshl_add_u64 v[2:3], v[2:3], 0, s[8:9]
	global_load_dword v202, v[2:3], off
	v_lshl_add_u64 v[2:3], v[2:3], 0, s[8:9]
	global_load_dword v203, v[2:3], off
	v_lshl_add_u64 v[2:3], v[2:3], 0, s[8:9]
	s_waitcnt vmcnt(32)
	ds_read_b128 v[74:77], v4 offset:272
	ds_read_b128 v[78:81], v4 offset:4368
	ds_read_b128 v[82:85], v4 offset:8464
	ds_read_b128 v[86:89], v4 offset:12560
	ds_read_b128 v[90:93], v4 offset:16656
	s_waitcnt lgkmcnt(5)
	v_pk_fma_f32 v[94:95], v[54:55], v[134:135], v[94:95]
	v_pk_fma_f32 v[94:95], v[56:57], v[136:137], v[94:95]
	v_pk_fma_f32 v[96:97], v[58:59], v[134:135], v[96:97]
	v_pk_fma_f32 v[96:97], v[60:61], v[136:137], v[96:97]
	v_pk_fma_f32 v[98:99], v[62:63], v[134:135], v[98:99]
	v_pk_fma_f32 v[98:99], v[64:65], v[136:137], v[98:99]
	v_pk_fma_f32 v[100:101], v[66:67], v[134:135], v[100:101]
	v_pk_fma_f32 v[100:101], v[68:69], v[136:137], v[100:101]
	v_pk_fma_f32 v[102:103], v[70:71], v[134:135], v[102:103]
	v_pk_fma_f32 v[102:103], v[72:73], v[136:137], v[102:103]
	ds_read_b128 v[54:57], v4 offset:288
	ds_read_b128 v[58:61], v4 offset:4384
	ds_read_b128 v[62:65], v4 offset:8480
	ds_read_b128 v[66:69], v4 offset:12576
	ds_read_b128 v[70:73], v4 offset:16672
	s_waitcnt lgkmcnt(5)
	v_pk_fma_f32 v[94:95], v[74:75], v[138:139], v[94:95]
	v_pk_fma_f32 v[94:95], v[76:77], v[140:141], v[94:95]
	v_pk_fma_f32 v[96:97], v[78:79], v[138:139], v[96:97]
	v_pk_fma_f32 v[96:97], v[80:81], v[140:141], v[96:97]
	v_pk_fma_f32 v[98:99], v[82:83], v[138:139], v[98:99]
	v_pk_fma_f32 v[98:99], v[84:85], v[140:141], v[98:99]
	v_pk_fma_f32 v[100:101], v[86:87], v[138:139], v[100:101]
	v_pk_fma_f32 v[100:101], v[88:89], v[140:141], v[100:101]
	v_pk_fma_f32 v[102:103], v[90:91], v[138:139], v[102:103]
	v_pk_fma_f32 v[102:103], v[92:93], v[140:141], v[102:103]
	ds_read_b128 v[74:77], v4 offset:304
	ds_read_b128 v[78:81], v4 offset:4400
	ds_read_b128 v[82:85], v4 offset:8496
	ds_read_b128 v[86:89], v4 offset:12592
	ds_read_b128 v[90:93], v4 offset:16688
	s_waitcnt lgkmcnt(5)
	v_pk_fma_f32 v[94:95], v[54:55], v[142:143], v[94:95]
	v_pk_fma_f32 v[94:95], v[56:57], v[144:145], v[94:95]
	v_pk_fma_f32 v[96:97], v[58:59], v[142:143], v[96:97]
	v_pk_fma_f32 v[96:97], v[60:61], v[144:145], v[96:97]
	v_pk_fma_f32 v[98:99], v[62:63], v[142:143], v[98:99]
	v_pk_fma_f32 v[98:99], v[64:65], v[144:145], v[98:99]
	v_pk_fma_f32 v[100:101], v[66:67], v[142:143], v[100:101]
	v_pk_fma_f32 v[100:101], v[68:69], v[144:145], v[100:101]
	v_pk_fma_f32 v[102:103], v[70:71], v[142:143], v[102:103]
	v_pk_fma_f32 v[102:103], v[72:73], v[144:145], v[102:103]
	ds_read_b128 v[54:57], v4 offset:320
	ds_read_b128 v[58:61], v4 offset:4416
	ds_read_b128 v[62:65], v4 offset:8512
	ds_read_b128 v[66:69], v4 offset:12608
	ds_read_b128 v[70:73], v4 offset:16704
	s_waitcnt lgkmcnt(5)
	v_pk_fma_f32 v[94:95], v[74:75], v[146:147], v[94:95]
	v_pk_fma_f32 v[94:95], v[76:77], v[148:149], v[94:95]
	v_pk_fma_f32 v[96:97], v[78:79], v[146:147], v[96:97]
	v_pk_fma_f32 v[96:97], v[80:81], v[148:149], v[96:97]
	v_pk_fma_f32 v[98:99], v[82:83], v[146:147], v[98:99]
	v_pk_fma_f32 v[98:99], v[84:85], v[148:149], v[98:99]
	v_pk_fma_f32 v[100:101], v[86:87], v[146:147], v[100:101]
	v_pk_fma_f32 v[100:101], v[88:89], v[148:149], v[100:101]
	v_pk_fma_f32 v[102:103], v[90:91], v[146:147], v[102:103]
	v_pk_fma_f32 v[102:103], v[92:93], v[148:149], v[102:103]
	ds_read_b128 v[74:77], v4 offset:336
	ds_read_b128 v[78:81], v4 offset:4432
	ds_read_b128 v[82:85], v4 offset:8528
	ds_read_b128 v[86:89], v4 offset:12624
	ds_read_b128 v[90:93], v4 offset:16720
	s_waitcnt lgkmcnt(5)
	v_pk_fma_f32 v[94:95], v[54:55], v[150:151], v[94:95]
	v_pk_fma_f32 v[94:95], v[56:57], v[152:153], v[94:95]
	v_pk_fma_f32 v[96:97], v[58:59], v[150:151], v[96:97]
	v_pk_fma_f32 v[96:97], v[60:61], v[152:153], v[96:97]
	v_pk_fma_f32 v[98:99], v[62:63], v[150:151], v[98:99]
	v_pk_fma_f32 v[98:99], v[64:65], v[152:153], v[98:99]
	v_pk_fma_f32 v[100:101], v[66:67], v[150:151], v[100:101]
	v_pk_fma_f32 v[100:101], v[68:69], v[152:153], v[100:101]
	v_pk_fma_f32 v[102:103], v[70:71], v[150:151], v[102:103]
	v_pk_fma_f32 v[102:103], v[72:73], v[152:153], v[102:103]
	ds_read_b128 v[54:57], v4 offset:352
	ds_read_b128 v[58:61], v4 offset:4448
	ds_read_b128 v[62:65], v4 offset:8544
	ds_read_b128 v[66:69], v4 offset:12640
	ds_read_b128 v[70:73], v4 offset:16736
	s_waitcnt lgkmcnt(5)
	v_pk_fma_f32 v[94:95], v[74:75], v[154:155], v[94:95]
	v_pk_fma_f32 v[94:95], v[76:77], v[156:157], v[94:95]
	v_pk_fma_f32 v[96:97], v[78:79], v[154:155], v[96:97]
	v_pk_fma_f32 v[96:97], v[80:81], v[156:157], v[96:97]
	v_pk_fma_f32 v[98:99], v[82:83], v[154:155], v[98:99]
	v_pk_fma_f32 v[98:99], v[84:85], v[156:157], v[98:99]
	v_pk_fma_f32 v[100:101], v[86:87], v[154:155], v[100:101]
	v_pk_fma_f32 v[100:101], v[88:89], v[156:157], v[100:101]
	v_pk_fma_f32 v[102:103], v[90:91], v[154:155], v[102:103]
	v_pk_fma_f32 v[102:103], v[92:93], v[156:157], v[102:103]
	ds_read_b128 v[74:77], v4 offset:368
	ds_read_b128 v[78:81], v4 offset:4464
	ds_read_b128 v[82:85], v4 offset:8560
	ds_read_b128 v[86:89], v4 offset:12656
	ds_read_b128 v[90:93], v4 offset:16752
	s_waitcnt lgkmcnt(5)
	v_pk_fma_f32 v[94:95], v[54:55], v[158:159], v[94:95]
	v_pk_fma_f32 v[94:95], v[56:57], v[160:161], v[94:95]
	v_pk_fma_f32 v[96:97], v[58:59], v[158:159], v[96:97]
	v_pk_fma_f32 v[96:97], v[60:61], v[160:161], v[96:97]
	v_pk_fma_f32 v[98:99], v[62:63], v[158:159], v[98:99]
	v_pk_fma_f32 v[98:99], v[64:65], v[160:161], v[98:99]
	v_pk_fma_f32 v[100:101], v[66:67], v[158:159], v[100:101]
	v_pk_fma_f32 v[100:101], v[68:69], v[160:161], v[100:101]
	v_pk_fma_f32 v[102:103], v[70:71], v[158:159], v[102:103]
	v_pk_fma_f32 v[102:103], v[72:73], v[160:161], v[102:103]
	ds_read_b128 v[54:57], v4 offset:384
	ds_read_b128 v[58:61], v4 offset:4480
	ds_read_b128 v[62:65], v4 offset:8576
	ds_read_b128 v[66:69], v4 offset:12672
	ds_read_b128 v[70:73], v4 offset:16768
	s_waitcnt lgkmcnt(5)
	v_pk_fma_f32 v[94:95], v[74:75], v[162:163], v[94:95]
	v_pk_fma_f32 v[94:95], v[76:77], v[164:165], v[94:95]
	v_pk_fma_f32 v[96:97], v[78:79], v[162:163], v[96:97]
	v_pk_fma_f32 v[96:97], v[80:81], v[164:165], v[96:97]
	v_pk_fma_f32 v[98:99], v[82:83], v[162:163], v[98:99]
	v_pk_fma_f32 v[98:99], v[84:85], v[164:165], v[98:99]
	v_pk_fma_f32 v[100:101], v[86:87], v[162:163], v[100:101]
	v_pk_fma_f32 v[100:101], v[88:89], v[164:165], v[100:101]
	v_pk_fma_f32 v[102:103], v[90:91], v[162:163], v[102:103]
	v_pk_fma_f32 v[102:103], v[92:93], v[164:165], v[102:103]
	global_load_dword v134, v[2:3], off
	v_lshl_add_u64 v[2:3], v[2:3], 0, s[8:9]
	global_load_dword v135, v[2:3], off
	v_lshl_add_u64 v[2:3], v[2:3], 0, s[8:9]
	global_load_dword v136, v[2:3], off
	v_lshl_add_u64 v[2:3], v[2:3], 0, s[8:9]
	global_load_dword v137, v[2:3], off
	v_lshl_add_u64 v[2:3], v[2:3], 0, s[8:9]
	global_load_dword v138, v[2:3], off
	v_lshl_add_u64 v[2:3], v[2:3], 0, s[8:9]
	global_load_dword v139, v[2:3], off
	v_lshl_add_u64 v[2:3], v[2:3], 0, s[8:9]
	global_load_dword v140, v[2:3], off
	v_lshl_add_u64 v[2:3], v[2:3], 0, s[8:9]
	global_load_dword v141, v[2:3], off
	v_lshl_add_u64 v[2:3], v[2:3], 0, s[8:9]
	global_load_dword v142, v[2:3], off
	v_lshl_add_u64 v[2:3], v[2:3], 0, s[8:9]
	global_load_dword v143, v[2:3], off
	v_lshl_add_u64 v[2:3], v[2:3], 0, s[8:9]
	global_load_dword v144, v[2:3], off
	v_lshl_add_u64 v[2:3], v[2:3], 0, s[8:9]
	global_load_dword v145, v[2:3], off
	v_lshl_add_u64 v[2:3], v[2:3], 0, s[8:9]
	global_load_dword v146, v[2:3], off
	v_lshl_add_u64 v[2:3], v[2:3], 0, s[8:9]
	global_load_dword v147, v[2:3], off
	v_lshl_add_u64 v[2:3], v[2:3], 0, s[8:9]
	global_load_dword v148, v[2:3], off
	v_lshl_add_u64 v[2:3], v[2:3], 0, s[8:9]
	global_load_dword v149, v[2:3], off
	v_lshl_add_u64 v[2:3], v[2:3], 0, s[8:9]
	global_load_dword v150, v[2:3], off
	v_lshl_add_u64 v[2:3], v[2:3], 0, s[8:9]
	global_load_dword v151, v[2:3], off
	v_lshl_add_u64 v[2:3], v[2:3], 0, s[8:9]
	global_load_dword v152, v[2:3], off
	v_lshl_add_u64 v[2:3], v[2:3], 0, s[8:9]
	global_load_dword v153, v[2:3], off
	v_lshl_add_u64 v[2:3], v[2:3], 0, s[8:9]
	global_load_dword v154, v[2:3], off
	v_lshl_add_u64 v[2:3], v[2:3], 0, s[8:9]
	global_load_dword v155, v[2:3], off
	v_lshl_add_u64 v[2:3], v[2:3], 0, s[8:9]
	global_load_dword v156, v[2:3], off
	v_lshl_add_u64 v[2:3], v[2:3], 0, s[8:9]
	global_load_dword v157, v[2:3], off
	v_lshl_add_u64 v[2:3], v[2:3], 0, s[8:9]
	global_load_dword v158, v[2:3], off
	v_lshl_add_u64 v[2:3], v[2:3], 0, s[8:9]
	global_load_dword v159, v[2:3], off
	v_lshl_add_u64 v[2:3], v[2:3], 0, s[8:9]
	global_load_dword v160, v[2:3], off
	v_lshl_add_u64 v[2:3], v[2:3], 0, s[8:9]
	global_load_dword v161, v[2:3], off
	v_lshl_add_u64 v[2:3], v[2:3], 0, s[8:9]
	global_load_dword v162, v[2:3], off
	v_lshl_add_u64 v[2:3], v[2:3], 0, s[8:9]
	global_load_dword v163, v[2:3], off
	v_lshl_add_u64 v[2:3], v[2:3], 0, s[8:9]
	global_load_dword v164, v[2:3], off
	v_lshl_add_u64 v[2:3], v[2:3], 0, s[8:9]
	global_load_dword v165, v[2:3], off
	v_lshl_add_u64 v[2:3], v[2:3], 0, s[8:9]
	s_waitcnt vmcnt(32)
	ds_read_b128 v[74:77], v4 offset:400
	ds_read_b128 v[78:81], v4 offset:4496
	ds_read_b128 v[82:85], v4 offset:8592
	ds_read_b128 v[86:89], v4 offset:12688
	ds_read_b128 v[90:93], v4 offset:16784
	s_waitcnt lgkmcnt(5)
	v_pk_fma_f32 v[94:95], v[54:55], v[172:173], v[94:95]
	v_pk_fma_f32 v[94:95], v[56:57], v[174:175], v[94:95]
	v_pk_fma_f32 v[96:97], v[58:59], v[172:173], v[96:97]
	v_pk_fma_f32 v[96:97], v[60:61], v[174:175], v[96:97]
	v_pk_fma_f32 v[98:99], v[62:63], v[172:173], v[98:99]
	v_pk_fma_f32 v[98:99], v[64:65], v[174:175], v[98:99]
	v_pk_fma_f32 v[100:101], v[66:67], v[172:173], v[100:101]
	v_pk_fma_f32 v[100:101], v[68:69], v[174:175], v[100:101]
	v_pk_fma_f32 v[102:103], v[70:71], v[172:173], v[102:103]
	v_pk_fma_f32 v[102:103], v[72:73], v[174:175], v[102:103]
	ds_read_b128 v[54:57], v4 offset:416
	ds_read_b128 v[58:61], v4 offset:4512
	ds_read_b128 v[62:65], v4 offset:8608
	ds_read_b128 v[66:69], v4 offset:12704
	ds_read_b128 v[70:73], v4 offset:16800
	s_waitcnt lgkmcnt(5)
	v_pk_fma_f32 v[94:95], v[74:75], v[176:177], v[94:95]
	v_pk_fma_f32 v[94:95], v[76:77], v[178:179], v[94:95]
	v_pk_fma_f32 v[96:97], v[78:79], v[176:177], v[96:97]
	v_pk_fma_f32 v[96:97], v[80:81], v[178:179], v[96:97]
	v_pk_fma_f32 v[98:99], v[82:83], v[176:177], v[98:99]
	v_pk_fma_f32 v[98:99], v[84:85], v[178:179], v[98:99]
	v_pk_fma_f32 v[100:101], v[86:87], v[176:177], v[100:101]
	v_pk_fma_f32 v[100:101], v[88:89], v[178:179], v[100:101]
	v_pk_fma_f32 v[102:103], v[90:91], v[176:177], v[102:103]
	v_pk_fma_f32 v[102:103], v[92:93], v[178:179], v[102:103]
	ds_read_b128 v[74:77], v4 offset:432
	ds_read_b128 v[78:81], v4 offset:4528
	ds_read_b128 v[82:85], v4 offset:8624
	ds_read_b128 v[86:89], v4 offset:12720
	ds_read_b128 v[90:93], v4 offset:16816
	s_waitcnt lgkmcnt(5)
	v_pk_fma_f32 v[94:95], v[54:55], v[180:181], v[94:95]
	v_pk_fma_f32 v[94:95], v[56:57], v[182:183], v[94:95]
	v_pk_fma_f32 v[96:97], v[58:59], v[180:181], v[96:97]
	v_pk_fma_f32 v[96:97], v[60:61], v[182:183], v[96:97]
	v_pk_fma_f32 v[98:99], v[62:63], v[180:181], v[98:99]
	v_pk_fma_f32 v[98:99], v[64:65], v[182:183], v[98:99]
	v_pk_fma_f32 v[100:101], v[66:67], v[180:181], v[100:101]
	v_pk_fma_f32 v[100:101], v[68:69], v[182:183], v[100:101]
	v_pk_fma_f32 v[102:103], v[70:71], v[180:181], v[102:103]
	v_pk_fma_f32 v[102:103], v[72:73], v[182:183], v[102:103]
	ds_read_b128 v[54:57], v4 offset:448
	ds_read_b128 v[58:61], v4 offset:4544
	ds_read_b128 v[62:65], v4 offset:8640
	ds_read_b128 v[66:69], v4 offset:12736
	ds_read_b128 v[70:73], v4 offset:16832
	s_waitcnt lgkmcnt(5)
	v_pk_fma_f32 v[94:95], v[74:75], v[184:185], v[94:95]
	v_pk_fma_f32 v[94:95], v[76:77], v[186:187], v[94:95]
	v_pk_fma_f32 v[96:97], v[78:79], v[184:185], v[96:97]
	v_pk_fma_f32 v[96:97], v[80:81], v[186:187], v[96:97]
	v_pk_fma_f32 v[98:99], v[82:83], v[184:185], v[98:99]
	v_pk_fma_f32 v[98:99], v[84:85], v[186:187], v[98:99]
	v_pk_fma_f32 v[100:101], v[86:87], v[184:185], v[100:101]
	v_pk_fma_f32 v[100:101], v[88:89], v[186:187], v[100:101]
	v_pk_fma_f32 v[102:103], v[90:91], v[184:185], v[102:103]
	v_pk_fma_f32 v[102:103], v[92:93], v[186:187], v[102:103]
	ds_read_b128 v[74:77], v4 offset:464
	ds_read_b128 v[78:81], v4 offset:4560
	ds_read_b128 v[82:85], v4 offset:8656
	ds_read_b128 v[86:89], v4 offset:12752
	ds_read_b128 v[90:93], v4 offset:16848
	s_waitcnt lgkmcnt(5)
	v_pk_fma_f32 v[94:95], v[54:55], v[188:189], v[94:95]
	v_pk_fma_f32 v[94:95], v[56:57], v[190:191], v[94:95]
	v_pk_fma_f32 v[96:97], v[58:59], v[188:189], v[96:97]
	v_pk_fma_f32 v[96:97], v[60:61], v[190:191], v[96:97]
	v_pk_fma_f32 v[98:99], v[62:63], v[188:189], v[98:99]
	v_pk_fma_f32 v[98:99], v[64:65], v[190:191], v[98:99]
	v_pk_fma_f32 v[100:101], v[66:67], v[188:189], v[100:101]
	v_pk_fma_f32 v[100:101], v[68:69], v[190:191], v[100:101]
	v_pk_fma_f32 v[102:103], v[70:71], v[188:189], v[102:103]
	v_pk_fma_f32 v[102:103], v[72:73], v[190:191], v[102:103]
	ds_read_b128 v[54:57], v4 offset:480
	ds_read_b128 v[58:61], v4 offset:4576
	ds_read_b128 v[62:65], v4 offset:8672
	ds_read_b128 v[66:69], v4 offset:12768
	ds_read_b128 v[70:73], v4 offset:16864
	s_waitcnt lgkmcnt(5)
	v_pk_fma_f32 v[94:95], v[74:75], v[192:193], v[94:95]
	v_pk_fma_f32 v[94:95], v[76:77], v[194:195], v[94:95]
	v_pk_fma_f32 v[96:97], v[78:79], v[192:193], v[96:97]
	v_pk_fma_f32 v[96:97], v[80:81], v[194:195], v[96:97]
	v_pk_fma_f32 v[98:99], v[82:83], v[192:193], v[98:99]
	v_pk_fma_f32 v[98:99], v[84:85], v[194:195], v[98:99]
	v_pk_fma_f32 v[100:101], v[86:87], v[192:193], v[100:101]
	v_pk_fma_f32 v[100:101], v[88:89], v[194:195], v[100:101]
	v_pk_fma_f32 v[102:103], v[90:91], v[192:193], v[102:103]
	v_pk_fma_f32 v[102:103], v[92:93], v[194:195], v[102:103]
	ds_read_b128 v[74:77], v4 offset:496
	ds_read_b128 v[78:81], v4 offset:4592
	ds_read_b128 v[82:85], v4 offset:8688
	ds_read_b128 v[86:89], v4 offset:12784
	ds_read_b128 v[90:93], v4 offset:16880
	s_waitcnt lgkmcnt(5)
	v_pk_fma_f32 v[94:95], v[54:55], v[196:197], v[94:95]
	v_pk_fma_f32 v[94:95], v[56:57], v[198:199], v[94:95]
	v_pk_fma_f32 v[96:97], v[58:59], v[196:197], v[96:97]
	v_pk_fma_f32 v[96:97], v[60:61], v[198:199], v[96:97]
	v_pk_fma_f32 v[98:99], v[62:63], v[196:197], v[98:99]
	v_pk_fma_f32 v[98:99], v[64:65], v[198:199], v[98:99]
	v_pk_fma_f32 v[100:101], v[66:67], v[196:197], v[100:101]
	v_pk_fma_f32 v[100:101], v[68:69], v[198:199], v[100:101]
	v_pk_fma_f32 v[102:103], v[70:71], v[196:197], v[102:103]
	v_pk_fma_f32 v[102:103], v[72:73], v[198:199], v[102:103]
	ds_read_b128 v[54:57], v4 offset:512
	ds_read_b128 v[58:61], v4 offset:4608
	ds_read_b128 v[62:65], v4 offset:8704
	ds_read_b128 v[66:69], v4 offset:12800
	ds_read_b128 v[70:73], v4 offset:16896
	s_waitcnt lgkmcnt(5)
	v_pk_fma_f32 v[94:95], v[74:75], v[200:201], v[94:95]
	v_pk_fma_f32 v[94:95], v[76:77], v[202:203], v[94:95]
	v_pk_fma_f32 v[96:97], v[78:79], v[200:201], v[96:97]
	v_pk_fma_f32 v[96:97], v[80:81], v[202:203], v[96:97]
	v_pk_fma_f32 v[98:99], v[82:83], v[200:201], v[98:99]
	v_pk_fma_f32 v[98:99], v[84:85], v[202:203], v[98:99]
	v_pk_fma_f32 v[100:101], v[86:87], v[200:201], v[100:101]
	v_pk_fma_f32 v[100:101], v[88:89], v[202:203], v[100:101]
	v_pk_fma_f32 v[102:103], v[90:91], v[200:201], v[102:103]
	v_pk_fma_f32 v[102:103], v[92:93], v[202:203], v[102:103]
	global_load_dword v172, v[2:3], off
	v_lshl_add_u64 v[2:3], v[2:3], 0, s[8:9]
	global_load_dword v173, v[2:3], off
	v_lshl_add_u64 v[2:3], v[2:3], 0, s[8:9]
	global_load_dword v174, v[2:3], off
	v_lshl_add_u64 v[2:3], v[2:3], 0, s[8:9]
	global_load_dword v175, v[2:3], off
	v_lshl_add_u64 v[2:3], v[2:3], 0, s[8:9]
	global_load_dword v176, v[2:3], off
	v_lshl_add_u64 v[2:3], v[2:3], 0, s[8:9]
	global_load_dword v177, v[2:3], off
	v_lshl_add_u64 v[2:3], v[2:3], 0, s[8:9]
	global_load_dword v178, v[2:3], off
	v_lshl_add_u64 v[2:3], v[2:3], 0, s[8:9]
	global_load_dword v179, v[2:3], off
	v_lshl_add_u64 v[2:3], v[2:3], 0, s[8:9]
	global_load_dword v180, v[2:3], off
	v_lshl_add_u64 v[2:3], v[2:3], 0, s[8:9]
	global_load_dword v181, v[2:3], off
	v_lshl_add_u64 v[2:3], v[2:3], 0, s[8:9]
	global_load_dword v182, v[2:3], off
	v_lshl_add_u64 v[2:3], v[2:3], 0, s[8:9]
	global_load_dword v183, v[2:3], off
	v_lshl_add_u64 v[2:3], v[2:3], 0, s[8:9]
	global_load_dword v184, v[2:3], off
	v_lshl_add_u64 v[2:3], v[2:3], 0, s[8:9]
	global_load_dword v185, v[2:3], off
	v_lshl_add_u64 v[2:3], v[2:3], 0, s[8:9]
	global_load_dword v186, v[2:3], off
	v_lshl_add_u64 v[2:3], v[2:3], 0, s[8:9]
	global_load_dword v187, v[2:3], off
	v_lshl_add_u64 v[2:3], v[2:3], 0, s[8:9]
	global_load_dword v188, v[2:3], off
	v_lshl_add_u64 v[2:3], v[2:3], 0, s[8:9]
	global_load_dword v189, v[2:3], off
	v_lshl_add_u64 v[2:3], v[2:3], 0, s[8:9]
	global_load_dword v190, v[2:3], off
	v_lshl_add_u64 v[2:3], v[2:3], 0, s[8:9]
	global_load_dword v191, v[2:3], off
	v_lshl_add_u64 v[2:3], v[2:3], 0, s[8:9]
	global_load_dword v192, v[2:3], off
	v_lshl_add_u64 v[2:3], v[2:3], 0, s[8:9]
	global_load_dword v193, v[2:3], off
	v_lshl_add_u64 v[2:3], v[2:3], 0, s[8:9]
	global_load_dword v194, v[2:3], off
	v_lshl_add_u64 v[2:3], v[2:3], 0, s[8:9]
	global_load_dword v195, v[2:3], off
	v_lshl_add_u64 v[2:3], v[2:3], 0, s[8:9]
	global_load_dword v196, v[2:3], off
	v_lshl_add_u64 v[2:3], v[2:3], 0, s[8:9]
	global_load_dword v197, v[2:3], off
	v_lshl_add_u64 v[2:3], v[2:3], 0, s[8:9]
	global_load_dword v198, v[2:3], off
	v_lshl_add_u64 v[2:3], v[2:3], 0, s[8:9]
	global_load_dword v199, v[2:3], off
	v_lshl_add_u64 v[2:3], v[2:3], 0, s[8:9]
	global_load_dword v200, v[2:3], off
	v_lshl_add_u64 v[2:3], v[2:3], 0, s[8:9]
	global_load_dword v201, v[2:3], off
	v_lshl_add_u64 v[2:3], v[2:3], 0, s[8:9]
	global_load_dword v202, v[2:3], off
	v_lshl_add_u64 v[2:3], v[2:3], 0, s[8:9]
	global_load_dword v203, v[2:3], off
	v_lshl_add_u64 v[2:3], v[2:3], 0, s[8:9]
	s_waitcnt vmcnt(32)
	ds_read_b128 v[74:77], v4 offset:528
	ds_read_b128 v[78:81], v4 offset:4624
	ds_read_b128 v[82:85], v4 offset:8720
	ds_read_b128 v[86:89], v4 offset:12816
	ds_read_b128 v[90:93], v4 offset:16912
	s_waitcnt lgkmcnt(5)
	v_pk_fma_f32 v[94:95], v[54:55], v[134:135], v[94:95]
	v_pk_fma_f32 v[94:95], v[56:57], v[136:137], v[94:95]
	v_pk_fma_f32 v[96:97], v[58:59], v[134:135], v[96:97]
	v_pk_fma_f32 v[96:97], v[60:61], v[136:137], v[96:97]
	v_pk_fma_f32 v[98:99], v[62:63], v[134:135], v[98:99]
	v_pk_fma_f32 v[98:99], v[64:65], v[136:137], v[98:99]
	v_pk_fma_f32 v[100:101], v[66:67], v[134:135], v[100:101]
	v_pk_fma_f32 v[100:101], v[68:69], v[136:137], v[100:101]
	v_pk_fma_f32 v[102:103], v[70:71], v[134:135], v[102:103]
	v_pk_fma_f32 v[102:103], v[72:73], v[136:137], v[102:103]
	ds_read_b128 v[54:57], v4 offset:544
	ds_read_b128 v[58:61], v4 offset:4640
	ds_read_b128 v[62:65], v4 offset:8736
	ds_read_b128 v[66:69], v4 offset:12832
	ds_read_b128 v[70:73], v4 offset:16928
	s_waitcnt lgkmcnt(5)
	v_pk_fma_f32 v[94:95], v[74:75], v[138:139], v[94:95]
	v_pk_fma_f32 v[94:95], v[76:77], v[140:141], v[94:95]
	v_pk_fma_f32 v[96:97], v[78:79], v[138:139], v[96:97]
	v_pk_fma_f32 v[96:97], v[80:81], v[140:141], v[96:97]
	v_pk_fma_f32 v[98:99], v[82:83], v[138:139], v[98:99]
	v_pk_fma_f32 v[98:99], v[84:85], v[140:141], v[98:99]
	v_pk_fma_f32 v[100:101], v[86:87], v[138:139], v[100:101]
	v_pk_fma_f32 v[100:101], v[88:89], v[140:141], v[100:101]
	v_pk_fma_f32 v[102:103], v[90:91], v[138:139], v[102:103]
	v_pk_fma_f32 v[102:103], v[92:93], v[140:141], v[102:103]
	ds_read_b128 v[74:77], v4 offset:560
	ds_read_b128 v[78:81], v4 offset:4656
	ds_read_b128 v[82:85], v4 offset:8752
	ds_read_b128 v[86:89], v4 offset:12848
	ds_read_b128 v[90:93], v4 offset:16944
	s_waitcnt lgkmcnt(5)
	v_pk_fma_f32 v[94:95], v[54:55], v[142:143], v[94:95]
	v_pk_fma_f32 v[94:95], v[56:57], v[144:145], v[94:95]
	v_pk_fma_f32 v[96:97], v[58:59], v[142:143], v[96:97]
	v_pk_fma_f32 v[96:97], v[60:61], v[144:145], v[96:97]
	v_pk_fma_f32 v[98:99], v[62:63], v[142:143], v[98:99]
	v_pk_fma_f32 v[98:99], v[64:65], v[144:145], v[98:99]
	v_pk_fma_f32 v[100:101], v[66:67], v[142:143], v[100:101]
	v_pk_fma_f32 v[100:101], v[68:69], v[144:145], v[100:101]
	v_pk_fma_f32 v[102:103], v[70:71], v[142:143], v[102:103]
	v_pk_fma_f32 v[102:103], v[72:73], v[144:145], v[102:103]
	ds_read_b128 v[54:57], v4 offset:576
	ds_read_b128 v[58:61], v4 offset:4672
	ds_read_b128 v[62:65], v4 offset:8768
	ds_read_b128 v[66:69], v4 offset:12864
	ds_read_b128 v[70:73], v4 offset:16960
	s_waitcnt lgkmcnt(5)
	v_pk_fma_f32 v[94:95], v[74:75], v[146:147], v[94:95]
	v_pk_fma_f32 v[94:95], v[76:77], v[148:149], v[94:95]
	v_pk_fma_f32 v[96:97], v[78:79], v[146:147], v[96:97]
	v_pk_fma_f32 v[96:97], v[80:81], v[148:149], v[96:97]
	v_pk_fma_f32 v[98:99], v[82:83], v[146:147], v[98:99]
	v_pk_fma_f32 v[98:99], v[84:85], v[148:149], v[98:99]
	v_pk_fma_f32 v[100:101], v[86:87], v[146:147], v[100:101]
	v_pk_fma_f32 v[100:101], v[88:89], v[148:149], v[100:101]
	v_pk_fma_f32 v[102:103], v[90:91], v[146:147], v[102:103]
	v_pk_fma_f32 v[102:103], v[92:93], v[148:149], v[102:103]
	ds_read_b128 v[74:77], v4 offset:592
	ds_read_b128 v[78:81], v4 offset:4688
	ds_read_b128 v[82:85], v4 offset:8784
	ds_read_b128 v[86:89], v4 offset:12880
	ds_read_b128 v[90:93], v4 offset:16976
	s_waitcnt lgkmcnt(5)
	v_pk_fma_f32 v[94:95], v[54:55], v[150:151], v[94:95]
	v_pk_fma_f32 v[94:95], v[56:57], v[152:153], v[94:95]
	v_pk_fma_f32 v[96:97], v[58:59], v[150:151], v[96:97]
	v_pk_fma_f32 v[96:97], v[60:61], v[152:153], v[96:97]
	v_pk_fma_f32 v[98:99], v[62:63], v[150:151], v[98:99]
	v_pk_fma_f32 v[98:99], v[64:65], v[152:153], v[98:99]
	v_pk_fma_f32 v[100:101], v[66:67], v[150:151], v[100:101]
	v_pk_fma_f32 v[100:101], v[68:69], v[152:153], v[100:101]
	v_pk_fma_f32 v[102:103], v[70:71], v[150:151], v[102:103]
	v_pk_fma_f32 v[102:103], v[72:73], v[152:153], v[102:103]
	ds_read_b128 v[54:57], v4 offset:608
	ds_read_b128 v[58:61], v4 offset:4704
	ds_read_b128 v[62:65], v4 offset:8800
	ds_read_b128 v[66:69], v4 offset:12896
	ds_read_b128 v[70:73], v4 offset:16992
	s_waitcnt lgkmcnt(5)
	v_pk_fma_f32 v[94:95], v[74:75], v[154:155], v[94:95]
	v_pk_fma_f32 v[94:95], v[76:77], v[156:157], v[94:95]
	v_pk_fma_f32 v[96:97], v[78:79], v[154:155], v[96:97]
	v_pk_fma_f32 v[96:97], v[80:81], v[156:157], v[96:97]
	v_pk_fma_f32 v[98:99], v[82:83], v[154:155], v[98:99]
	v_pk_fma_f32 v[98:99], v[84:85], v[156:157], v[98:99]
	v_pk_fma_f32 v[100:101], v[86:87], v[154:155], v[100:101]
	v_pk_fma_f32 v[100:101], v[88:89], v[156:157], v[100:101]
	v_pk_fma_f32 v[102:103], v[90:91], v[154:155], v[102:103]
	v_pk_fma_f32 v[102:103], v[92:93], v[156:157], v[102:103]
	ds_read_b128 v[74:77], v4 offset:624
	ds_read_b128 v[78:81], v4 offset:4720
	ds_read_b128 v[82:85], v4 offset:8816
	ds_read_b128 v[86:89], v4 offset:12912
	ds_read_b128 v[90:93], v4 offset:17008
	s_waitcnt lgkmcnt(5)
	v_pk_fma_f32 v[94:95], v[54:55], v[158:159], v[94:95]
	v_pk_fma_f32 v[94:95], v[56:57], v[160:161], v[94:95]
	v_pk_fma_f32 v[96:97], v[58:59], v[158:159], v[96:97]
	v_pk_fma_f32 v[96:97], v[60:61], v[160:161], v[96:97]
	v_pk_fma_f32 v[98:99], v[62:63], v[158:159], v[98:99]
	v_pk_fma_f32 v[98:99], v[64:65], v[160:161], v[98:99]
	v_pk_fma_f32 v[100:101], v[66:67], v[158:159], v[100:101]
	v_pk_fma_f32 v[100:101], v[68:69], v[160:161], v[100:101]
	v_pk_fma_f32 v[102:103], v[70:71], v[158:159], v[102:103]
	v_pk_fma_f32 v[102:103], v[72:73], v[160:161], v[102:103]
	ds_read_b128 v[54:57], v4 offset:640
	ds_read_b128 v[58:61], v4 offset:4736
	ds_read_b128 v[62:65], v4 offset:8832
	ds_read_b128 v[66:69], v4 offset:12928
	ds_read_b128 v[70:73], v4 offset:17024
	s_waitcnt lgkmcnt(5)
	v_pk_fma_f32 v[94:95], v[74:75], v[162:163], v[94:95]
	v_pk_fma_f32 v[94:95], v[76:77], v[164:165], v[94:95]
	v_pk_fma_f32 v[96:97], v[78:79], v[162:163], v[96:97]
	v_pk_fma_f32 v[96:97], v[80:81], v[164:165], v[96:97]
	v_pk_fma_f32 v[98:99], v[82:83], v[162:163], v[98:99]
	v_pk_fma_f32 v[98:99], v[84:85], v[164:165], v[98:99]
	v_pk_fma_f32 v[100:101], v[86:87], v[162:163], v[100:101]
	v_pk_fma_f32 v[100:101], v[88:89], v[164:165], v[100:101]
	v_pk_fma_f32 v[102:103], v[90:91], v[162:163], v[102:103]
	v_pk_fma_f32 v[102:103], v[92:93], v[164:165], v[102:103]
	global_load_dword v134, v[2:3], off
	v_lshl_add_u64 v[2:3], v[2:3], 0, s[8:9]
	global_load_dword v135, v[2:3], off
	v_lshl_add_u64 v[2:3], v[2:3], 0, s[8:9]
	global_load_dword v136, v[2:3], off
	v_lshl_add_u64 v[2:3], v[2:3], 0, s[8:9]
	global_load_dword v137, v[2:3], off
	v_lshl_add_u64 v[2:3], v[2:3], 0, s[8:9]
	global_load_dword v138, v[2:3], off
	v_lshl_add_u64 v[2:3], v[2:3], 0, s[8:9]
	global_load_dword v139, v[2:3], off
	v_lshl_add_u64 v[2:3], v[2:3], 0, s[8:9]
	global_load_dword v140, v[2:3], off
	v_lshl_add_u64 v[2:3], v[2:3], 0, s[8:9]
	global_load_dword v141, v[2:3], off
	v_lshl_add_u64 v[2:3], v[2:3], 0, s[8:9]
	global_load_dword v142, v[2:3], off
	v_lshl_add_u64 v[2:3], v[2:3], 0, s[8:9]
	global_load_dword v143, v[2:3], off
	v_lshl_add_u64 v[2:3], v[2:3], 0, s[8:9]
	global_load_dword v144, v[2:3], off
	v_lshl_add_u64 v[2:3], v[2:3], 0, s[8:9]
	global_load_dword v145, v[2:3], off
	v_lshl_add_u64 v[2:3], v[2:3], 0, s[8:9]
	global_load_dword v146, v[2:3], off
	v_lshl_add_u64 v[2:3], v[2:3], 0, s[8:9]
	global_load_dword v147, v[2:3], off
	v_lshl_add_u64 v[2:3], v[2:3], 0, s[8:9]
	global_load_dword v148, v[2:3], off
	v_lshl_add_u64 v[2:3], v[2:3], 0, s[8:9]
	global_load_dword v149, v[2:3], off
	v_lshl_add_u64 v[2:3], v[2:3], 0, s[8:9]
	global_load_dword v150, v[2:3], off
	v_lshl_add_u64 v[2:3], v[2:3], 0, s[8:9]
	global_load_dword v151, v[2:3], off
	v_lshl_add_u64 v[2:3], v[2:3], 0, s[8:9]
	global_load_dword v152, v[2:3], off
	v_lshl_add_u64 v[2:3], v[2:3], 0, s[8:9]
	global_load_dword v153, v[2:3], off
	v_lshl_add_u64 v[2:3], v[2:3], 0, s[8:9]
	global_load_dword v154, v[2:3], off
	v_lshl_add_u64 v[2:3], v[2:3], 0, s[8:9]
	global_load_dword v155, v[2:3], off
	v_lshl_add_u64 v[2:3], v[2:3], 0, s[8:9]
	global_load_dword v156, v[2:3], off
	v_lshl_add_u64 v[2:3], v[2:3], 0, s[8:9]
	global_load_dword v157, v[2:3], off
	v_lshl_add_u64 v[2:3], v[2:3], 0, s[8:9]
	global_load_dword v158, v[2:3], off
	v_lshl_add_u64 v[2:3], v[2:3], 0, s[8:9]
	global_load_dword v159, v[2:3], off
	v_lshl_add_u64 v[2:3], v[2:3], 0, s[8:9]
	global_load_dword v160, v[2:3], off
	v_lshl_add_u64 v[2:3], v[2:3], 0, s[8:9]
	global_load_dword v161, v[2:3], off
	v_lshl_add_u64 v[2:3], v[2:3], 0, s[8:9]
	global_load_dword v162, v[2:3], off
	v_lshl_add_u64 v[2:3], v[2:3], 0, s[8:9]
	global_load_dword v163, v[2:3], off
	v_lshl_add_u64 v[2:3], v[2:3], 0, s[8:9]
	global_load_dword v164, v[2:3], off
	v_lshl_add_u64 v[2:3], v[2:3], 0, s[8:9]
	global_load_dword v165, v[2:3], off
	v_lshl_add_u64 v[2:3], v[2:3], 0, s[8:9]
	s_waitcnt vmcnt(32)
	ds_read_b128 v[74:77], v4 offset:656
	ds_read_b128 v[78:81], v4 offset:4752
	ds_read_b128 v[82:85], v4 offset:8848
	ds_read_b128 v[86:89], v4 offset:12944
	ds_read_b128 v[90:93], v4 offset:17040
	s_waitcnt lgkmcnt(5)
	v_pk_fma_f32 v[94:95], v[54:55], v[172:173], v[94:95]
	v_pk_fma_f32 v[94:95], v[56:57], v[174:175], v[94:95]
	v_pk_fma_f32 v[96:97], v[58:59], v[172:173], v[96:97]
	v_pk_fma_f32 v[96:97], v[60:61], v[174:175], v[96:97]
	v_pk_fma_f32 v[98:99], v[62:63], v[172:173], v[98:99]
	v_pk_fma_f32 v[98:99], v[64:65], v[174:175], v[98:99]
	v_pk_fma_f32 v[100:101], v[66:67], v[172:173], v[100:101]
	v_pk_fma_f32 v[100:101], v[68:69], v[174:175], v[100:101]
	v_pk_fma_f32 v[102:103], v[70:71], v[172:173], v[102:103]
	v_pk_fma_f32 v[102:103], v[72:73], v[174:175], v[102:103]
	ds_read_b128 v[54:57], v4 offset:672
	ds_read_b128 v[58:61], v4 offset:4768
	ds_read_b128 v[62:65], v4 offset:8864
	ds_read_b128 v[66:69], v4 offset:12960
	ds_read_b128 v[70:73], v4 offset:17056
	s_waitcnt lgkmcnt(5)
	v_pk_fma_f32 v[94:95], v[74:75], v[176:177], v[94:95]
	v_pk_fma_f32 v[94:95], v[76:77], v[178:179], v[94:95]
	v_pk_fma_f32 v[96:97], v[78:79], v[176:177], v[96:97]
	v_pk_fma_f32 v[96:97], v[80:81], v[178:179], v[96:97]
	v_pk_fma_f32 v[98:99], v[82:83], v[176:177], v[98:99]
	v_pk_fma_f32 v[98:99], v[84:85], v[178:179], v[98:99]
	v_pk_fma_f32 v[100:101], v[86:87], v[176:177], v[100:101]
	v_pk_fma_f32 v[100:101], v[88:89], v[178:179], v[100:101]
	v_pk_fma_f32 v[102:103], v[90:91], v[176:177], v[102:103]
	v_pk_fma_f32 v[102:103], v[92:93], v[178:179], v[102:103]
	ds_read_b128 v[74:77], v4 offset:688
	ds_read_b128 v[78:81], v4 offset:4784
	ds_read_b128 v[82:85], v4 offset:8880
	ds_read_b128 v[86:89], v4 offset:12976
	ds_read_b128 v[90:93], v4 offset:17072
	s_waitcnt lgkmcnt(5)
	v_pk_fma_f32 v[94:95], v[54:55], v[180:181], v[94:95]
	v_pk_fma_f32 v[94:95], v[56:57], v[182:183], v[94:95]
	v_pk_fma_f32 v[96:97], v[58:59], v[180:181], v[96:97]
	v_pk_fma_f32 v[96:97], v[60:61], v[182:183], v[96:97]
	v_pk_fma_f32 v[98:99], v[62:63], v[180:181], v[98:99]
	v_pk_fma_f32 v[98:99], v[64:65], v[182:183], v[98:99]
	v_pk_fma_f32 v[100:101], v[66:67], v[180:181], v[100:101]
	v_pk_fma_f32 v[100:101], v[68:69], v[182:183], v[100:101]
	v_pk_fma_f32 v[102:103], v[70:71], v[180:181], v[102:103]
	v_pk_fma_f32 v[102:103], v[72:73], v[182:183], v[102:103]
	ds_read_b128 v[54:57], v4 offset:704
	ds_read_b128 v[58:61], v4 offset:4800
	ds_read_b128 v[62:65], v4 offset:8896
	ds_read_b128 v[66:69], v4 offset:12992
	ds_read_b128 v[70:73], v4 offset:17088
	s_waitcnt lgkmcnt(5)
	v_pk_fma_f32 v[94:95], v[74:75], v[184:185], v[94:95]
	v_pk_fma_f32 v[94:95], v[76:77], v[186:187], v[94:95]
	v_pk_fma_f32 v[96:97], v[78:79], v[184:185], v[96:97]
	v_pk_fma_f32 v[96:97], v[80:81], v[186:187], v[96:97]
	v_pk_fma_f32 v[98:99], v[82:83], v[184:185], v[98:99]
	v_pk_fma_f32 v[98:99], v[84:85], v[186:187], v[98:99]
	v_pk_fma_f32 v[100:101], v[86:87], v[184:185], v[100:101]
	v_pk_fma_f32 v[100:101], v[88:89], v[186:187], v[100:101]
	v_pk_fma_f32 v[102:103], v[90:91], v[184:185], v[102:103]
	v_pk_fma_f32 v[102:103], v[92:93], v[186:187], v[102:103]
	ds_read_b128 v[74:77], v4 offset:720
	ds_read_b128 v[78:81], v4 offset:4816
	ds_read_b128 v[82:85], v4 offset:8912
	ds_read_b128 v[86:89], v4 offset:13008
	ds_read_b128 v[90:93], v4 offset:17104
	s_waitcnt lgkmcnt(5)
	v_pk_fma_f32 v[94:95], v[54:55], v[188:189], v[94:95]
	v_pk_fma_f32 v[94:95], v[56:57], v[190:191], v[94:95]
	v_pk_fma_f32 v[96:97], v[58:59], v[188:189], v[96:97]
	v_pk_fma_f32 v[96:97], v[60:61], v[190:191], v[96:97]
	v_pk_fma_f32 v[98:99], v[62:63], v[188:189], v[98:99]
	v_pk_fma_f32 v[98:99], v[64:65], v[190:191], v[98:99]
	v_pk_fma_f32 v[100:101], v[66:67], v[188:189], v[100:101]
	v_pk_fma_f32 v[100:101], v[68:69], v[190:191], v[100:101]
	v_pk_fma_f32 v[102:103], v[70:71], v[188:189], v[102:103]
	v_pk_fma_f32 v[102:103], v[72:73], v[190:191], v[102:103]
	ds_read_b128 v[54:57], v4 offset:736
	ds_read_b128 v[58:61], v4 offset:4832
	ds_read_b128 v[62:65], v4 offset:8928
	ds_read_b128 v[66:69], v4 offset:13024
	ds_read_b128 v[70:73], v4 offset:17120
	s_waitcnt lgkmcnt(5)
	v_pk_fma_f32 v[94:95], v[74:75], v[192:193], v[94:95]
	v_pk_fma_f32 v[94:95], v[76:77], v[194:195], v[94:95]
	v_pk_fma_f32 v[96:97], v[78:79], v[192:193], v[96:97]
	v_pk_fma_f32 v[96:97], v[80:81], v[194:195], v[96:97]
	v_pk_fma_f32 v[98:99], v[82:83], v[192:193], v[98:99]
	v_pk_fma_f32 v[98:99], v[84:85], v[194:195], v[98:99]
	v_pk_fma_f32 v[100:101], v[86:87], v[192:193], v[100:101]
	v_pk_fma_f32 v[100:101], v[88:89], v[194:195], v[100:101]
	v_pk_fma_f32 v[102:103], v[90:91], v[192:193], v[102:103]
	v_pk_fma_f32 v[102:103], v[92:93], v[194:195], v[102:103]
	ds_read_b128 v[74:77], v4 offset:752
	ds_read_b128 v[78:81], v4 offset:4848
	ds_read_b128 v[82:85], v4 offset:8944
	ds_read_b128 v[86:89], v4 offset:13040
	ds_read_b128 v[90:93], v4 offset:17136
	s_waitcnt lgkmcnt(5)
	v_pk_fma_f32 v[94:95], v[54:55], v[196:197], v[94:95]
	v_pk_fma_f32 v[94:95], v[56:57], v[198:199], v[94:95]
	v_pk_fma_f32 v[96:97], v[58:59], v[196:197], v[96:97]
	v_pk_fma_f32 v[96:97], v[60:61], v[198:199], v[96:97]
	v_pk_fma_f32 v[98:99], v[62:63], v[196:197], v[98:99]
	v_pk_fma_f32 v[98:99], v[64:65], v[198:199], v[98:99]
	v_pk_fma_f32 v[100:101], v[66:67], v[196:197], v[100:101]
	v_pk_fma_f32 v[100:101], v[68:69], v[198:199], v[100:101]
	v_pk_fma_f32 v[102:103], v[70:71], v[196:197], v[102:103]
	v_pk_fma_f32 v[102:103], v[72:73], v[198:199], v[102:103]
	ds_read_b128 v[54:57], v4 offset:768
	ds_read_b128 v[58:61], v4 offset:4864
	ds_read_b128 v[62:65], v4 offset:8960
	ds_read_b128 v[66:69], v4 offset:13056
	ds_read_b128 v[70:73], v4 offset:17152
	s_waitcnt lgkmcnt(5)
	v_pk_fma_f32 v[94:95], v[74:75], v[200:201], v[94:95]
	v_pk_fma_f32 v[94:95], v[76:77], v[202:203], v[94:95]
	v_pk_fma_f32 v[96:97], v[78:79], v[200:201], v[96:97]
	v_pk_fma_f32 v[96:97], v[80:81], v[202:203], v[96:97]
	v_pk_fma_f32 v[98:99], v[82:83], v[200:201], v[98:99]
	v_pk_fma_f32 v[98:99], v[84:85], v[202:203], v[98:99]
	v_pk_fma_f32 v[100:101], v[86:87], v[200:201], v[100:101]
	v_pk_fma_f32 v[100:101], v[88:89], v[202:203], v[100:101]
	v_pk_fma_f32 v[102:103], v[90:91], v[200:201], v[102:103]
	v_pk_fma_f32 v[102:103], v[92:93], v[202:203], v[102:103]
	global_load_dword v172, v[2:3], off
	v_lshl_add_u64 v[2:3], v[2:3], 0, s[8:9]
	global_load_dword v173, v[2:3], off
	v_lshl_add_u64 v[2:3], v[2:3], 0, s[8:9]
	global_load_dword v174, v[2:3], off
	v_lshl_add_u64 v[2:3], v[2:3], 0, s[8:9]
	global_load_dword v175, v[2:3], off
	v_lshl_add_u64 v[2:3], v[2:3], 0, s[8:9]
	global_load_dword v176, v[2:3], off
	v_lshl_add_u64 v[2:3], v[2:3], 0, s[8:9]
	global_load_dword v177, v[2:3], off
	v_lshl_add_u64 v[2:3], v[2:3], 0, s[8:9]
	global_load_dword v178, v[2:3], off
	v_lshl_add_u64 v[2:3], v[2:3], 0, s[8:9]
	global_load_dword v179, v[2:3], off
	v_lshl_add_u64 v[2:3], v[2:3], 0, s[8:9]
	global_load_dword v180, v[2:3], off
	v_lshl_add_u64 v[2:3], v[2:3], 0, s[8:9]
	global_load_dword v181, v[2:3], off
	v_lshl_add_u64 v[2:3], v[2:3], 0, s[8:9]
	global_load_dword v182, v[2:3], off
	v_lshl_add_u64 v[2:3], v[2:3], 0, s[8:9]
	global_load_dword v183, v[2:3], off
	v_lshl_add_u64 v[2:3], v[2:3], 0, s[8:9]
	global_load_dword v184, v[2:3], off
	v_lshl_add_u64 v[2:3], v[2:3], 0, s[8:9]
	global_load_dword v185, v[2:3], off
	v_lshl_add_u64 v[2:3], v[2:3], 0, s[8:9]
	global_load_dword v186, v[2:3], off
	v_lshl_add_u64 v[2:3], v[2:3], 0, s[8:9]
	global_load_dword v187, v[2:3], off
	v_lshl_add_u64 v[2:3], v[2:3], 0, s[8:9]
	global_load_dword v188, v[2:3], off
	v_lshl_add_u64 v[2:3], v[2:3], 0, s[8:9]
	global_load_dword v189, v[2:3], off
	v_lshl_add_u64 v[2:3], v[2:3], 0, s[8:9]
	global_load_dword v190, v[2:3], off
	v_lshl_add_u64 v[2:3], v[2:3], 0, s[8:9]
	global_load_dword v191, v[2:3], off
	v_lshl_add_u64 v[2:3], v[2:3], 0, s[8:9]
	global_load_dword v192, v[2:3], off
	v_lshl_add_u64 v[2:3], v[2:3], 0, s[8:9]
	global_load_dword v193, v[2:3], off
	v_lshl_add_u64 v[2:3], v[2:3], 0, s[8:9]
	global_load_dword v194, v[2:3], off
	v_lshl_add_u64 v[2:3], v[2:3], 0, s[8:9]
	global_load_dword v195, v[2:3], off
	v_lshl_add_u64 v[2:3], v[2:3], 0, s[8:9]
	global_load_dword v196, v[2:3], off
	v_lshl_add_u64 v[2:3], v[2:3], 0, s[8:9]
	global_load_dword v197, v[2:3], off
	v_lshl_add_u64 v[2:3], v[2:3], 0, s[8:9]
	global_load_dword v198, v[2:3], off
	v_lshl_add_u64 v[2:3], v[2:3], 0, s[8:9]
	global_load_dword v199, v[2:3], off
	v_lshl_add_u64 v[2:3], v[2:3], 0, s[8:9]
	global_load_dword v200, v[2:3], off
	v_lshl_add_u64 v[2:3], v[2:3], 0, s[8:9]
	global_load_dword v201, v[2:3], off
	v_lshl_add_u64 v[2:3], v[2:3], 0, s[8:9]
	global_load_dword v202, v[2:3], off
	v_lshl_add_u64 v[2:3], v[2:3], 0, s[8:9]
	global_load_dword v203, v[2:3], off
	v_lshl_add_u64 v[2:3], v[2:3], 0, s[8:9]
	s_waitcnt vmcnt(32)
	ds_read_b128 v[74:77], v4 offset:784
	ds_read_b128 v[78:81], v4 offset:4880
	ds_read_b128 v[82:85], v4 offset:8976
	ds_read_b128 v[86:89], v4 offset:13072
	ds_read_b128 v[90:93], v4 offset:17168
	s_waitcnt lgkmcnt(5)
	v_pk_fma_f32 v[94:95], v[54:55], v[134:135], v[94:95]
	v_pk_fma_f32 v[94:95], v[56:57], v[136:137], v[94:95]
	v_pk_fma_f32 v[96:97], v[58:59], v[134:135], v[96:97]
	v_pk_fma_f32 v[96:97], v[60:61], v[136:137], v[96:97]
	v_pk_fma_f32 v[98:99], v[62:63], v[134:135], v[98:99]
	v_pk_fma_f32 v[98:99], v[64:65], v[136:137], v[98:99]
	v_pk_fma_f32 v[100:101], v[66:67], v[134:135], v[100:101]
	v_pk_fma_f32 v[100:101], v[68:69], v[136:137], v[100:101]
	v_pk_fma_f32 v[102:103], v[70:71], v[134:135], v[102:103]
	v_pk_fma_f32 v[102:103], v[72:73], v[136:137], v[102:103]
	ds_read_b128 v[54:57], v4 offset:800
	ds_read_b128 v[58:61], v4 offset:4896
	ds_read_b128 v[62:65], v4 offset:8992
	ds_read_b128 v[66:69], v4 offset:13088
	ds_read_b128 v[70:73], v4 offset:17184
	s_waitcnt lgkmcnt(5)
	v_pk_fma_f32 v[94:95], v[74:75], v[138:139], v[94:95]
	v_pk_fma_f32 v[94:95], v[76:77], v[140:141], v[94:95]
	v_pk_fma_f32 v[96:97], v[78:79], v[138:139], v[96:97]
	v_pk_fma_f32 v[96:97], v[80:81], v[140:141], v[96:97]
	v_pk_fma_f32 v[98:99], v[82:83], v[138:139], v[98:99]
	v_pk_fma_f32 v[98:99], v[84:85], v[140:141], v[98:99]
	v_pk_fma_f32 v[100:101], v[86:87], v[138:139], v[100:101]
	v_pk_fma_f32 v[100:101], v[88:89], v[140:141], v[100:101]
	v_pk_fma_f32 v[102:103], v[90:91], v[138:139], v[102:103]
	v_pk_fma_f32 v[102:103], v[92:93], v[140:141], v[102:103]
	ds_read_b128 v[74:77], v4 offset:816
	ds_read_b128 v[78:81], v4 offset:4912
	ds_read_b128 v[82:85], v4 offset:9008
	ds_read_b128 v[86:89], v4 offset:13104
	ds_read_b128 v[90:93], v4 offset:17200
	s_waitcnt lgkmcnt(5)
	v_pk_fma_f32 v[94:95], v[54:55], v[142:143], v[94:95]
	v_pk_fma_f32 v[94:95], v[56:57], v[144:145], v[94:95]
	v_pk_fma_f32 v[96:97], v[58:59], v[142:143], v[96:97]
	v_pk_fma_f32 v[96:97], v[60:61], v[144:145], v[96:97]
	v_pk_fma_f32 v[98:99], v[62:63], v[142:143], v[98:99]
	v_pk_fma_f32 v[98:99], v[64:65], v[144:145], v[98:99]
	v_pk_fma_f32 v[100:101], v[66:67], v[142:143], v[100:101]
	v_pk_fma_f32 v[100:101], v[68:69], v[144:145], v[100:101]
	v_pk_fma_f32 v[102:103], v[70:71], v[142:143], v[102:103]
	v_pk_fma_f32 v[102:103], v[72:73], v[144:145], v[102:103]
	ds_read_b128 v[54:57], v4 offset:832
	ds_read_b128 v[58:61], v4 offset:4928
	ds_read_b128 v[62:65], v4 offset:9024
	ds_read_b128 v[66:69], v4 offset:13120
	ds_read_b128 v[70:73], v4 offset:17216
	s_waitcnt lgkmcnt(5)
	v_pk_fma_f32 v[94:95], v[74:75], v[146:147], v[94:95]
	v_pk_fma_f32 v[94:95], v[76:77], v[148:149], v[94:95]
	v_pk_fma_f32 v[96:97], v[78:79], v[146:147], v[96:97]
	v_pk_fma_f32 v[96:97], v[80:81], v[148:149], v[96:97]
	v_pk_fma_f32 v[98:99], v[82:83], v[146:147], v[98:99]
	v_pk_fma_f32 v[98:99], v[84:85], v[148:149], v[98:99]
	v_pk_fma_f32 v[100:101], v[86:87], v[146:147], v[100:101]
	v_pk_fma_f32 v[100:101], v[88:89], v[148:149], v[100:101]
	v_pk_fma_f32 v[102:103], v[90:91], v[146:147], v[102:103]
	v_pk_fma_f32 v[102:103], v[92:93], v[148:149], v[102:103]
	ds_read_b128 v[74:77], v4 offset:848
	ds_read_b128 v[78:81], v4 offset:4944
	ds_read_b128 v[82:85], v4 offset:9040
	ds_read_b128 v[86:89], v4 offset:13136
	ds_read_b128 v[90:93], v4 offset:17232
	s_waitcnt lgkmcnt(5)
	v_pk_fma_f32 v[94:95], v[54:55], v[150:151], v[94:95]
	v_pk_fma_f32 v[94:95], v[56:57], v[152:153], v[94:95]
	v_pk_fma_f32 v[96:97], v[58:59], v[150:151], v[96:97]
	v_pk_fma_f32 v[96:97], v[60:61], v[152:153], v[96:97]
	v_pk_fma_f32 v[98:99], v[62:63], v[150:151], v[98:99]
	v_pk_fma_f32 v[98:99], v[64:65], v[152:153], v[98:99]
	v_pk_fma_f32 v[100:101], v[66:67], v[150:151], v[100:101]
	v_pk_fma_f32 v[100:101], v[68:69], v[152:153], v[100:101]
	v_pk_fma_f32 v[102:103], v[70:71], v[150:151], v[102:103]
	v_pk_fma_f32 v[102:103], v[72:73], v[152:153], v[102:103]
	ds_read_b128 v[54:57], v4 offset:864
	ds_read_b128 v[58:61], v4 offset:4960
	ds_read_b128 v[62:65], v4 offset:9056
	ds_read_b128 v[66:69], v4 offset:13152
	ds_read_b128 v[70:73], v4 offset:17248
	s_waitcnt lgkmcnt(5)
	v_pk_fma_f32 v[94:95], v[74:75], v[154:155], v[94:95]
	v_pk_fma_f32 v[94:95], v[76:77], v[156:157], v[94:95]
	v_pk_fma_f32 v[96:97], v[78:79], v[154:155], v[96:97]
	v_pk_fma_f32 v[96:97], v[80:81], v[156:157], v[96:97]
	v_pk_fma_f32 v[98:99], v[82:83], v[154:155], v[98:99]
	v_pk_fma_f32 v[98:99], v[84:85], v[156:157], v[98:99]
	v_pk_fma_f32 v[100:101], v[86:87], v[154:155], v[100:101]
	v_pk_fma_f32 v[100:101], v[88:89], v[156:157], v[100:101]
	v_pk_fma_f32 v[102:103], v[90:91], v[154:155], v[102:103]
	v_pk_fma_f32 v[102:103], v[92:93], v[156:157], v[102:103]
	ds_read_b128 v[74:77], v4 offset:880
	ds_read_b128 v[78:81], v4 offset:4976
	ds_read_b128 v[82:85], v4 offset:9072
	ds_read_b128 v[86:89], v4 offset:13168
	ds_read_b128 v[90:93], v4 offset:17264
	s_waitcnt lgkmcnt(5)
	v_pk_fma_f32 v[94:95], v[54:55], v[158:159], v[94:95]
	v_pk_fma_f32 v[94:95], v[56:57], v[160:161], v[94:95]
	v_pk_fma_f32 v[96:97], v[58:59], v[158:159], v[96:97]
	v_pk_fma_f32 v[96:97], v[60:61], v[160:161], v[96:97]
	v_pk_fma_f32 v[98:99], v[62:63], v[158:159], v[98:99]
	v_pk_fma_f32 v[98:99], v[64:65], v[160:161], v[98:99]
	v_pk_fma_f32 v[100:101], v[66:67], v[158:159], v[100:101]
	v_pk_fma_f32 v[100:101], v[68:69], v[160:161], v[100:101]
	v_pk_fma_f32 v[102:103], v[70:71], v[158:159], v[102:103]
	v_pk_fma_f32 v[102:103], v[72:73], v[160:161], v[102:103]
	ds_read_b128 v[54:57], v4 offset:896
	ds_read_b128 v[58:61], v4 offset:4992
	ds_read_b128 v[62:65], v4 offset:9088
	ds_read_b128 v[66:69], v4 offset:13184
	ds_read_b128 v[70:73], v4 offset:17280
	s_waitcnt lgkmcnt(5)
	v_pk_fma_f32 v[94:95], v[74:75], v[162:163], v[94:95]
	v_pk_fma_f32 v[94:95], v[76:77], v[164:165], v[94:95]
	v_pk_fma_f32 v[96:97], v[78:79], v[162:163], v[96:97]
	v_pk_fma_f32 v[96:97], v[80:81], v[164:165], v[96:97]
	v_pk_fma_f32 v[98:99], v[82:83], v[162:163], v[98:99]
	v_pk_fma_f32 v[98:99], v[84:85], v[164:165], v[98:99]
	v_pk_fma_f32 v[100:101], v[86:87], v[162:163], v[100:101]
	v_pk_fma_f32 v[100:101], v[88:89], v[164:165], v[100:101]
	v_pk_fma_f32 v[102:103], v[90:91], v[162:163], v[102:103]
	v_pk_fma_f32 v[102:103], v[92:93], v[164:165], v[102:103]
	s_waitcnt vmcnt(0)
	ds_read_b128 v[74:77], v4 offset:912
	ds_read_b128 v[78:81], v4 offset:5008
	ds_read_b128 v[82:85], v4 offset:9104
	ds_read_b128 v[86:89], v4 offset:13200
	ds_read_b128 v[90:93], v4 offset:17296
	s_waitcnt lgkmcnt(5)
	v_pk_fma_f32 v[94:95], v[54:55], v[172:173], v[94:95]
	v_pk_fma_f32 v[94:95], v[56:57], v[174:175], v[94:95]
	v_pk_fma_f32 v[96:97], v[58:59], v[172:173], v[96:97]
	v_pk_fma_f32 v[96:97], v[60:61], v[174:175], v[96:97]
	v_pk_fma_f32 v[98:99], v[62:63], v[172:173], v[98:99]
	v_pk_fma_f32 v[98:99], v[64:65], v[174:175], v[98:99]
	v_pk_fma_f32 v[100:101], v[66:67], v[172:173], v[100:101]
	v_pk_fma_f32 v[100:101], v[68:69], v[174:175], v[100:101]
	v_pk_fma_f32 v[102:103], v[70:71], v[172:173], v[102:103]
	v_pk_fma_f32 v[102:103], v[72:73], v[174:175], v[102:103]
	ds_read_b128 v[54:57], v4 offset:928
	ds_read_b128 v[58:61], v4 offset:5024
	ds_read_b128 v[62:65], v4 offset:9120
	ds_read_b128 v[66:69], v4 offset:13216
	ds_read_b128 v[70:73], v4 offset:17312
	s_waitcnt lgkmcnt(5)
	v_pk_fma_f32 v[94:95], v[74:75], v[176:177], v[94:95]
	v_pk_fma_f32 v[94:95], v[76:77], v[178:179], v[94:95]
	v_pk_fma_f32 v[96:97], v[78:79], v[176:177], v[96:97]
	v_pk_fma_f32 v[96:97], v[80:81], v[178:179], v[96:97]
	v_pk_fma_f32 v[98:99], v[82:83], v[176:177], v[98:99]
	v_pk_fma_f32 v[98:99], v[84:85], v[178:179], v[98:99]
	v_pk_fma_f32 v[100:101], v[86:87], v[176:177], v[100:101]
	v_pk_fma_f32 v[100:101], v[88:89], v[178:179], v[100:101]
	v_pk_fma_f32 v[102:103], v[90:91], v[176:177], v[102:103]
	v_pk_fma_f32 v[102:103], v[92:93], v[178:179], v[102:103]
	ds_read_b128 v[74:77], v4 offset:944
	ds_read_b128 v[78:81], v4 offset:5040
	ds_read_b128 v[82:85], v4 offset:9136
	ds_read_b128 v[86:89], v4 offset:13232
	ds_read_b128 v[90:93], v4 offset:17328
	s_waitcnt lgkmcnt(5)
	v_pk_fma_f32 v[94:95], v[54:55], v[180:181], v[94:95]
	v_pk_fma_f32 v[94:95], v[56:57], v[182:183], v[94:95]
	v_pk_fma_f32 v[96:97], v[58:59], v[180:181], v[96:97]
	v_pk_fma_f32 v[96:97], v[60:61], v[182:183], v[96:97]
	v_pk_fma_f32 v[98:99], v[62:63], v[180:181], v[98:99]
	v_pk_fma_f32 v[98:99], v[64:65], v[182:183], v[98:99]
	v_pk_fma_f32 v[100:101], v[66:67], v[180:181], v[100:101]
	v_pk_fma_f32 v[100:101], v[68:69], v[182:183], v[100:101]
	v_pk_fma_f32 v[102:103], v[70:71], v[180:181], v[102:103]
	v_pk_fma_f32 v[102:103], v[72:73], v[182:183], v[102:103]
	ds_read_b128 v[54:57], v4 offset:960
	ds_read_b128 v[58:61], v4 offset:5056
	ds_read_b128 v[62:65], v4 offset:9152
	ds_read_b128 v[66:69], v4 offset:13248
	ds_read_b128 v[70:73], v4 offset:17344
	s_waitcnt lgkmcnt(5)
	v_pk_fma_f32 v[94:95], v[74:75], v[184:185], v[94:95]
	v_pk_fma_f32 v[94:95], v[76:77], v[186:187], v[94:95]
	v_pk_fma_f32 v[96:97], v[78:79], v[184:185], v[96:97]
	v_pk_fma_f32 v[96:97], v[80:81], v[186:187], v[96:97]
	v_pk_fma_f32 v[98:99], v[82:83], v[184:185], v[98:99]
	v_pk_fma_f32 v[98:99], v[84:85], v[186:187], v[98:99]
	v_pk_fma_f32 v[100:101], v[86:87], v[184:185], v[100:101]
	v_pk_fma_f32 v[100:101], v[88:89], v[186:187], v[100:101]
	v_pk_fma_f32 v[102:103], v[90:91], v[184:185], v[102:103]
	v_pk_fma_f32 v[102:103], v[92:93], v[186:187], v[102:103]
	ds_read_b128 v[74:77], v4 offset:976
	ds_read_b128 v[78:81], v4 offset:5072
	ds_read_b128 v[82:85], v4 offset:9168
	ds_read_b128 v[86:89], v4 offset:13264
	ds_read_b128 v[90:93], v4 offset:17360
	s_waitcnt lgkmcnt(5)
	v_pk_fma_f32 v[94:95], v[54:55], v[188:189], v[94:95]
	v_pk_fma_f32 v[94:95], v[56:57], v[190:191], v[94:95]
	v_pk_fma_f32 v[96:97], v[58:59], v[188:189], v[96:97]
	v_pk_fma_f32 v[96:97], v[60:61], v[190:191], v[96:97]
	v_pk_fma_f32 v[98:99], v[62:63], v[188:189], v[98:99]
	v_pk_fma_f32 v[98:99], v[64:65], v[190:191], v[98:99]
	v_pk_fma_f32 v[100:101], v[66:67], v[188:189], v[100:101]
	v_pk_fma_f32 v[100:101], v[68:69], v[190:191], v[100:101]
	v_pk_fma_f32 v[102:103], v[70:71], v[188:189], v[102:103]
	v_pk_fma_f32 v[102:103], v[72:73], v[190:191], v[102:103]
	ds_read_b128 v[54:57], v4 offset:992
	ds_read_b128 v[58:61], v4 offset:5088
	ds_read_b128 v[62:65], v4 offset:9184
	ds_read_b128 v[66:69], v4 offset:13280
	ds_read_b128 v[70:73], v4 offset:17376
	s_waitcnt lgkmcnt(5)
	v_pk_fma_f32 v[94:95], v[74:75], v[192:193], v[94:95]
	v_pk_fma_f32 v[94:95], v[76:77], v[194:195], v[94:95]
	v_pk_fma_f32 v[96:97], v[78:79], v[192:193], v[96:97]
	v_pk_fma_f32 v[96:97], v[80:81], v[194:195], v[96:97]
	v_pk_fma_f32 v[98:99], v[82:83], v[192:193], v[98:99]
	v_pk_fma_f32 v[98:99], v[84:85], v[194:195], v[98:99]
	v_pk_fma_f32 v[100:101], v[86:87], v[192:193], v[100:101]
	v_pk_fma_f32 v[100:101], v[88:89], v[194:195], v[100:101]
	v_pk_fma_f32 v[102:103], v[90:91], v[192:193], v[102:103]
	v_pk_fma_f32 v[102:103], v[92:93], v[194:195], v[102:103]
	ds_read_b128 v[74:77], v4 offset:1008
	ds_read_b128 v[78:81], v4 offset:5104
	ds_read_b128 v[82:85], v4 offset:9200
	ds_read_b128 v[86:89], v4 offset:13296
	ds_read_b128 v[90:93], v4 offset:17392
	s_waitcnt lgkmcnt(5)
	v_pk_fma_f32 v[94:95], v[54:55], v[196:197], v[94:95]
	v_pk_fma_f32 v[94:95], v[56:57], v[198:199], v[94:95]
	v_pk_fma_f32 v[96:97], v[58:59], v[196:197], v[96:97]
	v_pk_fma_f32 v[96:97], v[60:61], v[198:199], v[96:97]
	v_pk_fma_f32 v[98:99], v[62:63], v[196:197], v[98:99]
	v_pk_fma_f32 v[98:99], v[64:65], v[198:199], v[98:99]
	v_pk_fma_f32 v[100:101], v[66:67], v[196:197], v[100:101]
	v_pk_fma_f32 v[100:101], v[68:69], v[198:199], v[100:101]
	v_pk_fma_f32 v[102:103], v[70:71], v[196:197], v[102:103]
	v_pk_fma_f32 v[102:103], v[72:73], v[198:199], v[102:103]
	s_waitcnt lgkmcnt(0)
	v_pk_fma_f32 v[94:95], v[74:75], v[200:201], v[94:95]
	v_pk_fma_f32 v[94:95], v[76:77], v[202:203], v[94:95]
	v_pk_fma_f32 v[96:97], v[78:79], v[200:201], v[96:97]
	v_pk_fma_f32 v[96:97], v[80:81], v[202:203], v[96:97]
	v_pk_fma_f32 v[98:99], v[82:83], v[200:201], v[98:99]
	v_pk_fma_f32 v[98:99], v[84:85], v[202:203], v[98:99]
	v_pk_fma_f32 v[100:101], v[86:87], v[200:201], v[100:101]
	v_pk_fma_f32 v[100:101], v[88:89], v[202:203], v[100:101]
	v_pk_fma_f32 v[102:103], v[90:91], v[200:201], v[102:103]
	v_pk_fma_f32 v[102:103], v[92:93], v[202:203], v[102:103]
	v_add_f32_e32 v20, v94, v95
	v_add_f32_e32 v21, v96, v97
	v_add_f32_e32 v22, v98, v99
	v_add_f32_e32 v23, v100, v101
	v_add_f32_e32 v12, v102, v103
	s_or_b64 exec, exec, s[0:1]
	s_movk_i32 s0, 0x500
	v_mul_lo_u32 v2, v32, s0
	v_lshl_or_b32 v2, v15, 2, v2
	v_cmp_gt_i32_e32 vcc, 64, v14
	ds_write2st64_b32 v2, v20, v21 offset0:80 offset1:81
	ds_write2st64_b32 v2, v22, v23 offset0:82 offset1:83
	ds_write_b32 v2, v12 offset:21504
	s_waitcnt lgkmcnt(0)
	s_barrier
	s_and_saveexec_b64 s[0:1], vcc
	s_cbranch_execz .LBB0_32
	v_lshlrev_b32_e32 v12, 2, v14
	ds_read2st64_b32 v[6:7], v12 offset0:80 offset1:81
	ds_read2st64_b32 v[8:9], v12 offset0:84 offset1:85
	s_mul_i32 s6, s3, 0x1800
	v_add_u32_e32 v2, s6, v16
	v_readlane_b32 s48, v210, 2
	v_ashrrev_i32_e32 v3, 31, v2
	v_readlane_b32 s58, v210, 12
	v_readlane_b32 s59, v210, 13
	s_waitcnt lgkmcnt(0)
	v_add_f32_e32 v6, v6, v9
	ds_read2st64_b32 v[18:19], v12 offset0:94 offset1:95
	v_lshl_add_u64 v[4:5], v[2:3], 2, s[58:59]
	global_load_dword v9, v[4:5], off
	v_lshl_add_u64 v[2:3], v[16:17], 2, s[90:91]
	ds_read2st64_b32 v[16:17], v12 offset0:90 offset1:91
	s_mul_i32 s3, s3, 5
	v_mad_i64_i32 v[20:21], s[6:7], s3, v27, v[2:3]
	s_add_i32 s6, s3, 1
	s_waitcnt lgkmcnt(0)
	v_add_f32_e32 v6, v6, v16
	v_add_f32_e32 v6, v6, v19
	v_readlane_b32 s49, v210, 3
	v_readlane_b32 s50, v210, 4
	v_readlane_b32 s51, v210, 5
	v_readlane_b32 s52, v210, 6
	v_readlane_b32 s53, v210, 7
	v_readlane_b32 s54, v210, 8
	v_readlane_b32 s55, v210, 9
	v_readlane_b32 s56, v210, 10
	v_readlane_b32 s57, v210, 11
	v_readlane_b32 s60, v210, 14
	v_readlane_b32 s61, v210, 15
	v_readlane_b32 s62, v210, 16
	v_readlane_b32 s63, v210, 17
	s_waitcnt vmcnt(0)
	v_add_f32_e32 v6, v6, v9
	global_store_dword v[20:21], v6, off
	ds_read2st64_b32 v[20:21], v12 offset0:86 offset1:87
	s_waitcnt lgkmcnt(0)
	v_add_f32_e32 v6, v7, v20
	v_add_f32_e32 v9, v6, v17
	ds_read2st64_b32 v[6:7], v12 offset0:96 offset1:97
	v_mad_i64_i32 v[16:17], s[6:7], s6, v27, v[2:3]
	s_add_i32 s6, s3, 2
	s_waitcnt lgkmcnt(0)
	v_add_f32_e32 v6, v9, v6
	global_load_dword v9, v[4:5], off
	s_waitcnt vmcnt(0)
	v_add_f32_e32 v6, v6, v9
	global_store_dword v[16:17], v6, off
	ds_read2st64_b32 v[16:17], v12 offset0:82 offset1:83
	s_waitcnt lgkmcnt(0)
	v_add_f32_e32 v6, v16, v21
	ds_read2st64_b32 v[20:21], v12 offset0:92 offset1:93
	s_waitcnt lgkmcnt(0)
	v_add_f32_e32 v6, v6, v20
	v_add_f32_e32 v6, v6, v7
	global_load_dword v7, v[4:5], off
	s_waitcnt vmcnt(0)
	v_add_f32_e32 v9, v6, v7
	v_mad_i64_i32 v[6:7], s[6:7], s6, v27, v[2:3]
	global_store_dword v[6:7], v9, off
	global_load_dword v9, v[4:5], off
	ds_read2st64_b32 v[6:7], v12 offset0:88 offset1:89
	s_add_i32 s6, s3, 3
	s_add_i32 s3, s3, 4
	s_waitcnt lgkmcnt(0)
	v_add_f32_e32 v6, v17, v6
	ds_read2st64_b32 v[16:17], v12 offset0:98 offset1:99
	v_add_f32_e32 v6, v6, v21
	v_mad_i64_i32 v[20:21], s[6:7], s6, v27, v[2:3]
	v_mad_i64_i32 v[2:3], s[6:7], s3, v27, v[2:3]
	s_waitcnt lgkmcnt(0)
	v_add_f32_e32 v6, v6, v16
	s_waitcnt vmcnt(0)
	v_add_f32_e32 v6, v6, v9
	global_store_dword v[20:21], v6, off
	global_load_dword v4, v[4:5], off
	v_add_f32_e32 v6, v8, v7
	v_add_f32_e32 v6, v6, v18
	v_add_f32_e32 v6, v6, v17
	s_waitcnt vmcnt(0)
	v_add_f32_e32 v4, v6, v4
	global_store_dword v[2:3], v4, off
